# cross-attention: row sum-of-squares load issued before the q-tile K loop; hgrn-kv: dropped the full vmcnt wait before the first input loads
# baseline (speedup 1.0000x reference)
.LBB0_466:
	v_lshlrev_b32_e32 v2, 1, v165
	v_and_b32_e32 v1, 0x7e, v2
	s_cmpk_lt_i32 s94, 0x400
	v_and_b32_e32 v10, 0xf8, v33
	s_cselect_b64 s[0:1], -1, 0
	s_cmpk_gt_i32 s94, 0x3ff
	v_and_b32_e32 v52, 0x78, v29
	v_mov_b32_e32 v27, 0
	v_and_b32_e32 v53, 62, v2
	v_lshlrev_b32_e32 v26, 1, v1
	v_lshlrev_b32_e32 v28, 1, v10
	s_cbranch_scc1 .LBB0_468
	s_lshl_b32 s2, s94, 3
	s_lshl_b32 s3, s94, 6
	s_and_b32 s2, s2, 0xfffff800
	s_and_b32 s3, s3, 0x7c0
	s_or_b32 s18, s2, s3
	v_add_u32_e32 v2, s18, v52
	s_nop 0
	v_ashrrev_i32_e32 v3, 31, v2
	s_lshl_b32 s2, s94, 2
	v_lshlrev_b64 v[4:5], 13, v[2:3]
	v_or_b32_e32 v6, 1, v2
	v_or_b32_e32 v8, 2, v2
	v_or_b32_e32 v12, 3, v2
	v_or_b32_e32 v14, 4, v2
	v_or_b32_e32 v16, 5, v2
	v_or_b32_e32 v32, 6, v2
	v_or_b32_e32 v2, 7, v2
	s_and_b32 s19, s2, 0x380
	v_ashrrev_i32_e32 v7, 31, v6
	v_ashrrev_i32_e32 v9, 31, v8
	v_ashrrev_i32_e32 v13, 31, v12
	v_ashrrev_i32_e32 v15, 31, v14
	v_ashrrev_i32_e32 v17, 31, v16
	v_ashrrev_i32_e32 v33, 31, v32
	v_ashrrev_i32_e32 v3, 31, v2
	v_or_b32_e32 v34, s18, v53
	v_lshl_add_u64 v[4:5], s[64:65], 0, v[4:5]
	s_lshl_b32 s2, s19, 1
	s_mov_b32 s3, 0
	v_lshlrev_b64 v[6:7], 13, v[6:7]
	v_lshlrev_b64 v[8:9], 13, v[8:9]
	v_lshlrev_b64 v[12:13], 13, v[12:13]
	v_lshlrev_b64 v[14:15], 13, v[14:15]
	v_lshlrev_b64 v[16:17], 13, v[16:17]
	v_lshlrev_b64 v[32:33], 13, v[32:33]
	v_lshlrev_b64 v[2:3], 13, v[2:3]
	v_ashrrev_i32_e32 v35, 31, v34
	v_lshl_add_u64 v[4:5], v[4:5], 0, s[2:3]
	v_lshl_add_u64 v[6:7], s[64:65], 0, v[6:7]
	v_lshl_add_u64 v[8:9], s[64:65], 0, v[8:9]
	v_lshl_add_u64 v[12:13], s[64:65], 0, v[12:13]
	v_lshl_add_u64 v[14:15], s[64:65], 0, v[14:15]
	v_lshl_add_u64 v[16:17], s[64:65], 0, v[16:17]
	v_lshl_add_u64 v[32:33], s[64:65], 0, v[32:33]
	v_lshl_add_u64 v[2:3], s[64:65], 0, v[2:3]
	v_lshlrev_b64 v[34:35], 13, v[34:35]
	v_lshl_add_u64 v[4:5], v[4:5], 0, v[26:27]
	v_lshl_add_u64 v[6:7], v[6:7], 0, s[2:3]
	v_lshl_add_u64 v[8:9], v[8:9], 0, s[2:3]
	v_lshl_add_u64 v[12:13], v[12:13], 0, s[2:3]
	v_lshl_add_u64 v[14:15], v[14:15], 0, s[2:3]
	v_lshl_add_u64 v[16:17], v[16:17], 0, s[2:3]
	v_lshl_add_u64 v[32:33], v[32:33], 0, s[2:3]
	v_lshl_add_u64 v[2:3], v[2:3], 0, s[2:3]
	v_lshl_add_u64 v[34:35], s[64:65], 0, v[34:35]
	v_lshl_add_u64 v[6:7], v[6:7], 0, v[26:27]
	v_lshl_add_u64 v[8:9], v[8:9], 0, v[26:27]
	v_lshl_add_u64 v[12:13], v[12:13], 0, v[26:27]
	v_lshl_add_u64 v[14:15], v[14:15], 0, v[26:27]
	v_lshl_add_u64 v[16:17], v[16:17], 0, v[26:27]
	v_lshl_add_u64 v[32:33], v[32:33], 0, v[26:27]
	v_lshl_add_u64 v[2:3], v[2:3], 0, v[26:27]
	v_lshl_add_u64 v[34:35], v[34:35], 0, s[2:3]
	v_mov_b32_e32 v29, v27
	global_load_dword v56, v[4:5], off offset:2048
	global_load_dword v57, v[6:7], off offset:2048
	global_load_dword v58, v[8:9], off offset:2048
	global_load_dword v59, v[12:13], off offset:2048
	global_load_dword v60, v[14:15], off offset:2048
	global_load_dword v61, v[16:17], off offset:2048
	global_load_dword v62, v[32:33], off offset:2048
	global_load_dword v63, v[2:3], off offset:2048
	v_lshl_add_u64 v[34:35], v[34:35], 0, v[28:29]
	v_add_co_u32_e32 v2, vcc, 0x1000, v34
	v_or_b32_e32 v11, s19, v1
	s_nop 0
	v_addc_co_u32_e32 v3, vcc, 0, v35, vcc
	v_add_co_u32_e32 v4, vcc, 0x3000, v34
	v_readlane_b32 s90, v228, 10
	v_lshlrev_b32_e32 v11, 2, v11
	v_addc_co_u32_e32 v5, vcc, 0, v35, vcc
	v_readlane_b32 s91, v228, 11
	global_load_dwordx4 v[6:9], v[4:5], off
	s_nop 0
	global_load_dwordx4 v[2:5], v[2:3], off
	v_readlane_b32 s58, v228, 12
	v_readlane_b32 s59, v228, 13
	global_load_dwordx2 v[34:35], v11, s[90:91]
	v_readlane_b32 s56, v228, 8
	v_readlane_b32 s57, v228, 9
	s_andn2_b64 vcc, exec, s[0:1]
	s_cbranch_vccz .LBB0_469
	s_branch .LBB0_541

.LBB0_1113:
	s_lshl_b32 s0, s3, 12
	s_and_b32 s6, s0, 0x180000
	s_ashr_i32 s2, s27, 6
	s_lshl_b32 s0, s27, 7
	s_lshl_b32 s15, s2, 11
	s_and_b32 s0, s0, 0x780
	s_or_b32 s12, s15, s0
	s_lshl_b32 s0, s27, 3
	s_and_b32 s14, s0, 0x180
	v_lshl_add_u64 v[136:137], v[128:129], 0, s[6:7]
	s_lshl_b32 s6, s14, 12
	s_ashr_i32 s13, s12, 31
	v_lshl_add_u64 v[242:243], s[12:13], 2, v[126:127]
	global_load_dwordx4 v[244:247], v[242:243], off
	v_lshl_add_u64 v[2:3], v[102:103], 0, s[6:7]
	s_lshl_b64 s[0:1], s[12:13], 12
	v_add_co_u32_e32 v4, vcc, s17, v2
	v_lshl_add_u64 v[6:7], v[100:101], 0, s[0:1]
	s_nop 0
	v_addc_co_u32_e32 v5, vcc, 0, v3, vcc
	global_load_dwordx4 v[50:53], v[6:7], off
	global_load_dwordx4 v[54:57], v[6:7], off offset:64
	global_load_dwordx4 v[58:61], v[2:3], off
	global_load_dwordx4 v[46:49], v[2:3], off offset:128
	global_load_dwordx4 v[62:65], v[4:5], off
	global_load_dwordx4 v[42:45], v[4:5], off offset:128
	global_load_dwordx4 v[34:37], v[6:7], off offset:128
	global_load_dwordx4 v[38:41], v[6:7], off offset:192
	global_load_dwordx4 v[18:21], v[6:7], off offset:256
	global_load_dwordx4 v[22:25], v[6:7], off offset:320
	global_load_dwordx4 v[26:29], v[2:3], off offset:256
	global_load_dwordx4 v[10:13], v[2:3], off offset:384
	global_load_dwordx4 v[30:33], v[4:5], off offset:256
	global_load_dwordx4 v[14:17], v[4:5], off offset:384
	s_nop 0
	global_load_dwordx4 v[2:5], v[6:7], off offset:384
	s_nop 0
	global_load_dwordx4 v[6:9], v[6:7], off offset:448
	s_and_b32 s0, s11, 0x780
	s_or_b32 s0, s15, s0
	s_ashr_i32 s1, s0, 31
	s_lshl_b64 s[0:1], s[0:1], 12
	v_lshl_add_u64 v[138:139], v[130:131], 0, s[0:1]
	s_mov_b64 s[0:1], 0
	v_mov_b32_e32 v94, 0
	v_mov_b32_e32 v95, v99
	v_mov_b32_e32 v96, v99
	v_mov_b32_e32 v97, v99
	v_mov_b32_e32 v90, 0
	v_mov_b32_e32 v91, v99
	v_mov_b32_e32 v92, v99
	v_mov_b32_e32 v93, v99
	v_mov_b32_e32 v86, 0
	v_mov_b32_e32 v87, v99
	v_mov_b32_e32 v88, v99
	v_mov_b32_e32 v89, v99
	v_mov_b32_e32 v82, 0
	v_mov_b32_e32 v83, v99
	v_mov_b32_e32 v84, v99
	v_mov_b32_e32 v85, v99
	v_mov_b32_e32 v78, 0
	v_mov_b32_e32 v79, v99
	v_mov_b32_e32 v80, v99
	v_mov_b32_e32 v81, v99
	v_mov_b32_e32 v70, 0
	v_mov_b32_e32 v71, v99
	v_mov_b32_e32 v72, v99
	v_mov_b32_e32 v73, v99
	v_mov_b32_e32 v66, 0
	v_mov_b32_e32 v67, v99
	v_mov_b32_e32 v68, v99
	v_mov_b32_e32 v69, v99
	v_mov_b32_e32 v74, 0
	v_mov_b32_e32 v75, v99
	v_mov_b32_e32 v76, v99
	v_mov_b32_e32 v77, v99
	s_barrier
.LBB0_1114:
	s_waitcnt vmcnt(15)
	v_mov_b64_e32 v[182:183], v[52:53]
	v_mov_b64_e32 v[180:181], v[50:51]
	v_lshl_add_u64 v[50:51], v[136:137], 0, s[0:1]
	v_add_co_u32_e32 v222, vcc, s18, v50
	s_waitcnt vmcnt(14)
	v_mov_b64_e32 v[178:179], v[56:57]
	v_addc_co_u32_e32 v223, vcc, 0, v51, vcc
	s_waitcnt vmcnt(13)
	ds_write_b128 v173, v[58:61]
	s_waitcnt vmcnt(11)
	ds_write_b128 v173, v[62:65] offset:9216
	v_lshl_add_u64 v[220:221], v[138:139], 0, s[0:1]
	v_add_co_u32_e32 v224, vcc, s19, v50
	v_mov_b64_e32 v[176:177], v[54:55]
	s_nop 0
	v_addc_co_u32_e32 v225, vcc, 0, v51, vcc
	global_load_dwordx4 v[50:53], v[220:221], off offset:-256
	global_load_dwordx4 v[54:57], v[220:221], off offset:-192
	global_load_dwordx4 v[58:61], v[222:223], off offset:512
	global_load_dwordx4 v[62:65], v[224:225], off offset:512
	s_waitcnt lgkmcnt(0)
	s_barrier
	ds_read_b128 v[184:187], v1
	ds_read_b128 v[188:191], v1 offset:64
	s_waitcnt lgkmcnt(1)
	v_mfma_f32_16x16x32_bf16 v[94:97], v[180:183], v[184:187], v[94:97]
	ds_read_b128 v[184:187], v1 offset:2304
	ds_read_b128 v[192:195], v1 offset:2368
	s_add_u32 s0, s0, 0x200
	s_addc_u32 s1, s1, 0
	s_waitcnt lgkmcnt(1)
	v_mfma_f32_16x16x32_bf16 v[90:93], v[180:183], v[184:187], v[90:93]
	ds_read_b128 v[184:187], v1 offset:4608
	ds_read_b128 v[196:199], v1 offset:4672
	s_cmpk_lg_i32 s0, 0xe00
	s_waitcnt lgkmcnt(1)
	v_mfma_f32_16x16x32_bf16 v[86:89], v[180:183], v[184:187], v[86:89]
	ds_read_b128 v[184:187], v1 offset:6912
	ds_read_b128 v[200:203], v1 offset:6976
	s_waitcnt lgkmcnt(1)
	v_mfma_f32_16x16x32_bf16 v[82:85], v[180:183], v[184:187], v[82:85]
	ds_read_b128 v[184:187], v1 offset:9216
	ds_read_b128 v[204:207], v1 offset:9280
	s_waitcnt lgkmcnt(1)
	v_mfma_f32_16x16x32_bf16 v[78:81], v[180:183], v[184:187], v[78:81]
	ds_read_b128 v[184:187], v1 offset:11520
	ds_read_b128 v[208:211], v1 offset:11584
	s_waitcnt lgkmcnt(1)
	v_mfma_f32_16x16x32_bf16 v[70:73], v[180:183], v[184:187], v[70:73]
	ds_read_b128 v[184:187], v1 offset:13824
	ds_read_b128 v[212:215], v1 offset:13888
	s_waitcnt lgkmcnt(1)
	v_mfma_f32_16x16x32_bf16 v[66:69], v[180:183], v[184:187], v[66:69]
	ds_read_b128 v[184:187], v1 offset:16128
	ds_read_b128 v[216:219], v1 offset:16192
	ds_write_b128 v173, v[46:49] offset:18432
	s_waitcnt vmcnt(14)
	ds_write_b128 v173, v[42:45] offset:27648
	global_load_dwordx4 v[46:49], v[222:223], off offset:640
	s_waitcnt lgkmcnt(3)
	v_mfma_f32_16x16x32_bf16 v[74:77], v[180:183], v[184:187], v[74:77]
	s_waitcnt vmcnt(14)
	v_mov_b64_e32 v[186:187], v[36:37]
	s_waitcnt vmcnt(13)
	v_mov_b64_e32 v[182:183], v[40:41]
	v_mov_b64_e32 v[184:185], v[34:35]
	v_mfma_f32_16x16x32_bf16 v[94:97], v[176:179], v[188:191], v[94:97]
	v_mov_b64_e32 v[180:181], v[38:39]
	global_load_dwordx4 v[42:45], v[224:225], off offset:640
	global_load_dwordx4 v[34:37], v[220:221], off offset:-128
	global_load_dwordx4 v[38:41], v[220:221], off offset:-64
	s_waitcnt lgkmcnt(0)
	v_mfma_f32_16x16x32_bf16 v[90:93], v[176:179], v[192:195], v[90:93]
	s_barrier
	v_mfma_f32_16x16x32_bf16 v[86:89], v[176:179], v[196:199], v[86:89]
	v_mfma_f32_16x16x32_bf16 v[82:85], v[176:179], v[200:203], v[82:85]
	v_mfma_f32_16x16x32_bf16 v[78:81], v[176:179], v[204:207], v[78:81]
	v_mfma_f32_16x16x32_bf16 v[70:73], v[176:179], v[208:211], v[70:73]
	v_mfma_f32_16x16x32_bf16 v[66:69], v[176:179], v[212:215], v[66:69]
	v_mfma_f32_16x16x32_bf16 v[74:77], v[176:179], v[216:219], v[74:77]
	ds_read_b128 v[176:179], v1 offset:18432
	ds_read_b128 v[188:191], v1 offset:18496
	s_waitcnt lgkmcnt(1)
	v_mfma_f32_16x16x32_bf16 v[94:97], v[184:187], v[176:179], v[94:97]
	ds_read_b128 v[176:179], v1 offset:20736
	ds_read_b128 v[192:195], v1 offset:20800
	s_waitcnt lgkmcnt(1)
	v_mfma_f32_16x16x32_bf16 v[90:93], v[184:187], v[176:179], v[90:93]
	ds_read_b128 v[176:179], v1 offset:23040
	ds_read_b128 v[196:199], v1 offset:23104
	s_waitcnt lgkmcnt(1)
	v_mfma_f32_16x16x32_bf16 v[86:89], v[184:187], v[176:179], v[86:89]
	ds_read_b128 v[176:179], v1 offset:25344
	ds_read_b128 v[200:203], v1 offset:25408
	s_waitcnt lgkmcnt(1)
	v_mfma_f32_16x16x32_bf16 v[82:85], v[184:187], v[176:179], v[82:85]
	ds_read_b128 v[176:179], v1 offset:27648
	ds_read_b128 v[204:207], v1 offset:27712
	s_waitcnt lgkmcnt(1)
	v_mfma_f32_16x16x32_bf16 v[78:81], v[184:187], v[176:179], v[78:81]
	ds_read_b128 v[176:179], v1 offset:29952
	ds_read_b128 v[208:211], v1 offset:30016
	s_waitcnt lgkmcnt(1)
	v_mfma_f32_16x16x32_bf16 v[70:73], v[184:187], v[176:179], v[70:73]
	ds_read_b128 v[176:179], v1 offset:32256
	ds_read_b128 v[212:215], v1 offset:32320
	s_waitcnt lgkmcnt(1)
	v_mfma_f32_16x16x32_bf16 v[66:69], v[184:187], v[176:179], v[66:69]
	ds_read_b128 v[176:179], v1 offset:34560
	ds_read_b128 v[216:219], v1 offset:34624
	s_waitcnt vmcnt(13)
	ds_write_b128 v173, v[26:29]
	s_waitcnt vmcnt(11)
	ds_write_b128 v173, v[30:33] offset:9216
	global_load_dwordx4 v[26:29], v[222:223], off offset:768
	s_waitcnt lgkmcnt(3)
	v_mfma_f32_16x16x32_bf16 v[74:77], v[184:187], v[176:179], v[74:77]
	v_mov_b64_e32 v[186:187], v[20:21]
	v_mov_b64_e32 v[178:179], v[24:25]
	v_mov_b64_e32 v[184:185], v[18:19]
	v_mfma_f32_16x16x32_bf16 v[94:97], v[180:183], v[188:191], v[94:97]
	v_mov_b64_e32 v[176:177], v[22:23]
	global_load_dwordx4 v[30:33], v[224:225], off offset:768
	global_load_dwordx4 v[18:21], v[220:221], off
	global_load_dwordx4 v[22:25], v[220:221], off offset:64
	s_waitcnt lgkmcnt(0)
	v_mfma_f32_16x16x32_bf16 v[90:93], v[180:183], v[192:195], v[90:93]
	s_barrier
	v_mfma_f32_16x16x32_bf16 v[86:89], v[180:183], v[196:199], v[86:89]
	v_mfma_f32_16x16x32_bf16 v[82:85], v[180:183], v[200:203], v[82:85]
	v_mfma_f32_16x16x32_bf16 v[78:81], v[180:183], v[204:207], v[78:81]
	v_mfma_f32_16x16x32_bf16 v[70:73], v[180:183], v[208:211], v[70:73]
	v_mfma_f32_16x16x32_bf16 v[66:69], v[180:183], v[212:215], v[66:69]
	v_mfma_f32_16x16x32_bf16 v[74:77], v[180:183], v[216:219], v[74:77]
	ds_read_b128 v[180:183], v1
	ds_read_b128 v[188:191], v1 offset:64
	s_waitcnt lgkmcnt(1)
	v_mfma_f32_16x16x32_bf16 v[94:97], v[184:187], v[180:183], v[94:97]
	ds_read_b128 v[180:183], v1 offset:2304
	ds_read_b128 v[192:195], v1 offset:2368
	s_waitcnt lgkmcnt(1)
	v_mfma_f32_16x16x32_bf16 v[90:93], v[184:187], v[180:183], v[90:93]
	ds_read_b128 v[180:183], v1 offset:4608
	ds_read_b128 v[196:199], v1 offset:4672
	s_waitcnt lgkmcnt(1)
	v_mfma_f32_16x16x32_bf16 v[86:89], v[184:187], v[180:183], v[86:89]
	ds_read_b128 v[180:183], v1 offset:6912
	ds_read_b128 v[200:203], v1 offset:6976
	s_waitcnt lgkmcnt(1)
	v_mfma_f32_16x16x32_bf16 v[82:85], v[184:187], v[180:183], v[82:85]
	ds_read_b128 v[180:183], v1 offset:9216
	ds_read_b128 v[204:207], v1 offset:9280
	s_waitcnt lgkmcnt(1)
	v_mfma_f32_16x16x32_bf16 v[78:81], v[184:187], v[180:183], v[78:81]
	ds_read_b128 v[180:183], v1 offset:11520
	ds_read_b128 v[208:211], v1 offset:11584
	s_waitcnt lgkmcnt(1)
	v_mfma_f32_16x16x32_bf16 v[70:73], v[184:187], v[180:183], v[70:73]
	ds_read_b128 v[180:183], v1 offset:13824
	ds_read_b128 v[212:215], v1 offset:13888
	s_waitcnt lgkmcnt(1)
	v_mfma_f32_16x16x32_bf16 v[66:69], v[184:187], v[180:183], v[66:69]
	ds_read_b128 v[180:183], v1 offset:16128
	ds_read_b128 v[216:219], v1 offset:16192
	ds_write_b128 v173, v[10:13] offset:18432
	s_waitcnt vmcnt(14)
	ds_write_b128 v173, v[14:17] offset:27648
	global_load_dwordx4 v[10:13], v[222:223], off offset:896
	s_waitcnt lgkmcnt(3)
	v_mfma_f32_16x16x32_bf16 v[74:77], v[184:187], v[180:183], v[74:77]
	s_waitcnt vmcnt(13)
	v_mov_b64_e32 v[182:183], v[8:9]
	v_mov_b64_e32 v[186:187], v[4:5]
	v_mov_b64_e32 v[180:181], v[6:7]
	v_mov_b64_e32 v[184:185], v[2:3]
	global_load_dwordx4 v[14:17], v[224:225], off offset:896
	global_load_dwordx4 v[2:5], v[220:221], off offset:128
	global_load_dwordx4 v[6:9], v[220:221], off offset:192
	v_mfma_f32_16x16x32_bf16 v[94:97], v[176:179], v[188:191], v[94:97]
	s_waitcnt lgkmcnt(0)
	s_barrier
	v_mfma_f32_16x16x32_bf16 v[90:93], v[176:179], v[192:195], v[90:93]
	v_mfma_f32_16x16x32_bf16 v[86:89], v[176:179], v[196:199], v[86:89]
	v_mfma_f32_16x16x32_bf16 v[82:85], v[176:179], v[200:203], v[82:85]
	v_mfma_f32_16x16x32_bf16 v[78:81], v[176:179], v[204:207], v[78:81]
	v_mfma_f32_16x16x32_bf16 v[70:73], v[176:179], v[208:211], v[70:73]
	v_mfma_f32_16x16x32_bf16 v[66:69], v[176:179], v[212:215], v[66:69]
	v_mfma_f32_16x16x32_bf16 v[74:77], v[176:179], v[216:219], v[74:77]
	ds_read_b128 v[176:179], v1 offset:18432
	ds_read_b128 v[188:191], v1 offset:18496
	s_waitcnt lgkmcnt(1)
	v_mfma_f32_16x16x32_bf16 v[94:97], v[184:187], v[176:179], v[94:97]
	ds_read_b128 v[176:179], v1 offset:20736
	ds_read_b128 v[192:195], v1 offset:20800
	s_waitcnt lgkmcnt(1)
	v_mfma_f32_16x16x32_bf16 v[90:93], v[184:187], v[176:179], v[90:93]
	ds_read_b128 v[176:179], v1 offset:23040
	ds_read_b128 v[196:199], v1 offset:23104
	s_waitcnt lgkmcnt(1)
	v_mfma_f32_16x16x32_bf16 v[86:89], v[184:187], v[176:179], v[86:89]
	ds_read_b128 v[176:179], v1 offset:25344
	ds_read_b128 v[200:203], v1 offset:25408
	s_waitcnt lgkmcnt(1)
	v_mfma_f32_16x16x32_bf16 v[82:85], v[184:187], v[176:179], v[82:85]
	ds_read_b128 v[176:179], v1 offset:27648
	ds_read_b128 v[204:207], v1 offset:27712
	s_waitcnt lgkmcnt(1)
	v_mfma_f32_16x16x32_bf16 v[78:81], v[184:187], v[176:179], v[78:81]
	ds_read_b128 v[176:179], v1 offset:29952
	ds_read_b128 v[208:211], v1 offset:30016
	s_waitcnt lgkmcnt(1)
	v_mfma_f32_16x16x32_bf16 v[70:73], v[184:187], v[176:179], v[70:73]
	ds_read_b128 v[176:179], v1 offset:32256
	ds_read_b128 v[212:215], v1 offset:32320
	s_waitcnt lgkmcnt(1)
	v_mfma_f32_16x16x32_bf16 v[66:69], v[184:187], v[176:179], v[66:69]
	ds_read_b128 v[176:179], v1 offset:34560
	ds_read_b128 v[216:219], v1 offset:34624
	s_waitcnt lgkmcnt(1)
	v_mfma_f32_16x16x32_bf16 v[74:77], v[184:187], v[176:179], v[74:77]
	v_mfma_f32_16x16x32_bf16 v[94:97], v[180:183], v[188:191], v[94:97]
	v_mfma_f32_16x16x32_bf16 v[90:93], v[180:183], v[192:195], v[90:93]
	v_mfma_f32_16x16x32_bf16 v[86:89], v[180:183], v[196:199], v[86:89]
	v_mfma_f32_16x16x32_bf16 v[82:85], v[180:183], v[200:203], v[82:85]
	v_mfma_f32_16x16x32_bf16 v[78:81], v[180:183], v[204:207], v[78:81]
	v_mfma_f32_16x16x32_bf16 v[70:73], v[180:183], v[208:211], v[70:73]
	v_mfma_f32_16x16x32_bf16 v[66:69], v[180:183], v[212:215], v[66:69]
	s_waitcnt lgkmcnt(0)
	v_mfma_f32_16x16x32_bf16 v[74:77], v[180:183], v[216:219], v[74:77]
	s_cbranch_scc1 .LBB0_1114
	s_waitcnt vmcnt(13)
	ds_write_b128 v173, v[58:61]
	s_waitcnt vmcnt(12)
	ds_write_b128 v173, v[62:65] offset:9216
	s_waitcnt lgkmcnt(0)
	s_barrier
	ds_read_b128 v[58:61], v1
	ds_read_b128 v[62:65], v1 offset:64
	s_waitcnt lgkmcnt(1)
	v_mfma_f32_16x16x32_bf16 v[58:61], v[50:53], v[58:61], v[94:97]
	s_lshl_b32 s0, s2, 8
	s_bitset1_b32 s0, 7
	s_ashr_i32 s1, s0, 31
	s_waitcnt lgkmcnt(0)
	v_mfma_f32_16x16x32_bf16 v[58:61], v[54:57], v[62:65], v[58:61]
	ds_read_b128 v[62:65], v1 offset:2304
	ds_read_b128 v[94:97], v1 offset:2368
	s_lshl_b64 s[0:1], s[0:1], 11
	s_add_u32 s0, s46, s0
	s_waitcnt lgkmcnt(1)
	v_mfma_f32_16x16x32_bf16 v[62:65], v[50:53], v[62:65], v[90:93]
	s_addc_u32 s1, s47, s1
	s_lshl_b32 s2, s14, 1
	s_add_u32 s14, s0, s2
	s_waitcnt lgkmcnt(0)
	v_mfma_f32_16x16x32_bf16 v[62:65], v[54:57], v[94:97], v[62:65]
	ds_read_b128 v[90:93], v1 offset:4608
	ds_read_b128 v[94:97], v1 offset:4672
	s_addc_u32 s15, s1, 0
	s_waitcnt lgkmcnt(1)
	v_mfma_f32_16x16x32_bf16 v[86:89], v[50:53], v[90:93], v[86:89]
	s_waitcnt lgkmcnt(0)
	v_mfma_f32_16x16x32_bf16 v[86:89], v[54:57], v[94:97], v[86:89]
	ds_read_b128 v[90:93], v1 offset:6912
	ds_read_b128 v[94:97], v1 offset:6976
	s_waitcnt lgkmcnt(1)
	v_mfma_f32_16x16x32_bf16 v[82:85], v[50:53], v[90:93], v[82:85]
	s_waitcnt lgkmcnt(0)
	v_mfma_f32_16x16x32_bf16 v[82:85], v[54:57], v[94:97], v[82:85]
	ds_read_b128 v[90:93], v1 offset:9216
	ds_read_b128 v[94:97], v1 offset:9280
	s_waitcnt lgkmcnt(1)
	v_mfma_f32_16x16x32_bf16 v[78:81], v[50:53], v[90:93], v[78:81]
	s_waitcnt lgkmcnt(0)
	v_mfma_f32_16x16x32_bf16 v[78:81], v[54:57], v[94:97], v[78:81]
	ds_read_b128 v[90:93], v1 offset:11520
	ds_read_b128 v[94:97], v1 offset:11584
	s_waitcnt lgkmcnt(1)
	v_mfma_f32_16x16x32_bf16 v[70:73], v[50:53], v[90:93], v[70:73]
	s_waitcnt lgkmcnt(0)
	v_mfma_f32_16x16x32_bf16 v[70:73], v[54:57], v[94:97], v[70:73]
	ds_read_b128 v[90:93], v1 offset:13824
	ds_read_b128 v[94:97], v1 offset:13888
	s_waitcnt lgkmcnt(1)
	v_mfma_f32_16x16x32_bf16 v[66:69], v[50:53], v[90:93], v[66:69]
	s_waitcnt lgkmcnt(0)
	v_mfma_f32_16x16x32_bf16 v[66:69], v[54:57], v[94:97], v[66:69]
	ds_read_b128 v[90:93], v1 offset:16128
	ds_read_b128 v[94:97], v1 offset:16192
	s_waitcnt vmcnt(11)
	ds_write_b128 v173, v[46:49] offset:18432
	s_waitcnt vmcnt(10)
	ds_write_b128 v173, v[42:45] offset:27648
	s_waitcnt lgkmcnt(0)
	s_barrier
	ds_read_b128 v[42:45], v1 offset:18432
	ds_read_b128 v[46:49], v1 offset:18496
	v_mfma_f32_16x16x32_bf16 v[50:53], v[50:53], v[90:93], v[74:77]
	s_waitcnt vmcnt(9) lgkmcnt(1)
	v_mfma_f32_16x16x32_bf16 v[42:45], v[34:37], v[42:45], v[58:61]
	v_mfma_f32_16x16x32_bf16 v[50:53], v[54:57], v[94:97], v[50:53]
	s_waitcnt vmcnt(8) lgkmcnt(0)
	v_mfma_f32_16x16x32_bf16 v[42:45], v[38:41], v[46:49], v[42:45]
	ds_read_b128 v[46:49], v1 offset:20736
	ds_read_b128 v[54:57], v1 offset:20800
	s_waitcnt lgkmcnt(1)
	v_mfma_f32_16x16x32_bf16 v[46:49], v[34:37], v[46:49], v[62:65]
	s_waitcnt lgkmcnt(0)
	v_mfma_f32_16x16x32_bf16 v[46:49], v[38:41], v[54:57], v[46:49]
	ds_read_b128 v[54:57], v1 offset:23040
	ds_read_b128 v[58:61], v1 offset:23104
	s_waitcnt lgkmcnt(1)
	v_mfma_f32_16x16x32_bf16 v[54:57], v[34:37], v[54:57], v[86:89]
	s_waitcnt lgkmcnt(0)
	v_mfma_f32_16x16x32_bf16 v[54:57], v[38:41], v[58:61], v[54:57]
	ds_read_b128 v[58:61], v1 offset:25344
	ds_read_b128 v[62:65], v1 offset:25408
	s_waitcnt lgkmcnt(1)
	v_mfma_f32_16x16x32_bf16 v[58:61], v[34:37], v[58:61], v[82:85]
	s_waitcnt lgkmcnt(0)
	v_mfma_f32_16x16x32_bf16 v[58:61], v[38:41], v[62:65], v[58:61]
	ds_read_b128 v[62:65], v1 offset:27648
	ds_read_b128 v[74:77], v1 offset:27712
	s_waitcnt lgkmcnt(1)
	v_mfma_f32_16x16x32_bf16 v[62:65], v[34:37], v[62:65], v[78:81]
	s_waitcnt lgkmcnt(0)
	v_mfma_f32_16x16x32_bf16 v[62:65], v[38:41], v[74:77], v[62:65]
	ds_read_b128 v[74:77], v1 offset:29952
	ds_read_b128 v[78:81], v1 offset:30016
	s_waitcnt lgkmcnt(1)
	v_mfma_f32_16x16x32_bf16 v[70:73], v[34:37], v[74:77], v[70:73]
	s_waitcnt lgkmcnt(0)
	v_mfma_f32_16x16x32_bf16 v[70:73], v[38:41], v[78:81], v[70:73]
	ds_read_b128 v[74:77], v1 offset:32256
	ds_read_b128 v[78:81], v1 offset:32320
	s_waitcnt lgkmcnt(1)
	v_mfma_f32_16x16x32_bf16 v[66:69], v[34:37], v[74:77], v[66:69]
	s_waitcnt lgkmcnt(0)
	v_mfma_f32_16x16x32_bf16 v[66:69], v[38:41], v[78:81], v[66:69]
	ds_read_b128 v[74:77], v1 offset:34560
	ds_read_b128 v[78:81], v1 offset:34624
	s_waitcnt vmcnt(7)
	ds_write_b128 v173, v[26:29]
	s_waitcnt vmcnt(6)
	ds_write_b128 v173, v[30:33] offset:9216
	s_waitcnt lgkmcnt(0)
	s_barrier
	ds_read_b128 v[26:29], v1
	ds_read_b128 v[30:33], v1 offset:64
	v_mfma_f32_16x16x32_bf16 v[34:37], v[34:37], v[74:77], v[50:53]
	v_lshl_add_u64 v[74:75], s[14:15], 0, v[98:99]
	s_waitcnt vmcnt(5) lgkmcnt(1)
	v_mfma_f32_16x16x32_bf16 v[26:29], v[18:21], v[26:29], v[42:45]
	v_mfma_f32_16x16x32_bf16 v[34:37], v[38:41], v[78:81], v[34:37]
	v_lshl_add_u64 v[78:79], v[74:75], 0, v[124:125]
	s_waitcnt vmcnt(4) lgkmcnt(0)
	v_mfma_f32_16x16x32_bf16 v[26:29], v[22:25], v[30:33], v[26:29]
	ds_read_b128 v[30:33], v1 offset:2304
	ds_read_b128 v[38:41], v1 offset:2368
	s_waitcnt lgkmcnt(1)
	v_mfma_f32_16x16x32_bf16 v[30:33], v[18:21], v[30:33], v[46:49]
	s_waitcnt lgkmcnt(0)
	v_mfma_f32_16x16x32_bf16 v[30:33], v[22:25], v[38:41], v[30:33]
	ds_read_b128 v[38:41], v1 offset:4608
	ds_read_b128 v[42:45], v1 offset:4672
	s_waitcnt lgkmcnt(1)
	v_mfma_f32_16x16x32_bf16 v[38:41], v[18:21], v[38:41], v[54:57]
	s_waitcnt lgkmcnt(0)
	v_mfma_f32_16x16x32_bf16 v[38:41], v[22:25], v[42:45], v[38:41]
	ds_read_b128 v[42:45], v1 offset:6912
	ds_read_b128 v[46:49], v1 offset:6976
	s_waitcnt lgkmcnt(1)
	v_mfma_f32_16x16x32_bf16 v[42:45], v[18:21], v[42:45], v[58:61]
	s_waitcnt lgkmcnt(0)
	v_mfma_f32_16x16x32_bf16 v[42:45], v[22:25], v[46:49], v[42:45]
	ds_read_b128 v[46:49], v1 offset:9216
	ds_read_b128 v[50:53], v1 offset:9280
	s_waitcnt lgkmcnt(1)
	v_mfma_f32_16x16x32_bf16 v[46:49], v[18:21], v[46:49], v[62:65]
	s_waitcnt lgkmcnt(0)
	v_mfma_f32_16x16x32_bf16 v[46:49], v[22:25], v[50:53], v[46:49]
	ds_read_b128 v[50:53], v1 offset:11520
	ds_read_b128 v[54:57], v1 offset:11584
	s_waitcnt lgkmcnt(1)
	v_mfma_f32_16x16x32_bf16 v[50:53], v[18:21], v[50:53], v[70:73]
	s_waitcnt lgkmcnt(0)
	v_mfma_f32_16x16x32_bf16 v[50:53], v[22:25], v[54:57], v[50:53]
	ds_read_b128 v[54:57], v1 offset:13824
	ds_read_b128 v[58:61], v1 offset:13888
	s_waitcnt lgkmcnt(1)
	v_mfma_f32_16x16x32_bf16 v[54:57], v[18:21], v[54:57], v[66:69]
	s_nop 2
	v_lshl_add_u64 v[66:67], v[74:75], 0, v[122:123]
	s_waitcnt lgkmcnt(0)
	v_mfma_f32_16x16x32_bf16 v[54:57], v[22:25], v[58:61], v[54:57]
	ds_read_b128 v[58:61], v1 offset:16128
	ds_read_b128 v[62:65], v1 offset:16192
	s_waitcnt vmcnt(3)
	ds_write_b128 v173, v[10:13] offset:18432
	s_waitcnt vmcnt(2)
	ds_write_b128 v173, v[14:17] offset:27648
	s_waitcnt lgkmcnt(0)
	s_barrier
	ds_read_b128 v[10:13], v1 offset:18432
	ds_read_b128 v[14:17], v1 offset:18496
	s_waitcnt vmcnt(1) lgkmcnt(1)
	v_mfma_f32_16x16x32_bf16 v[10:13], v[2:5], v[10:13], v[26:29]
	v_mfma_f32_16x16x32_bf16 v[18:21], v[18:21], v[58:61], v[34:37]
	s_waitcnt vmcnt(0) lgkmcnt(0)
	v_mfma_f32_16x16x32_bf16 v[34:37], v[6:9], v[14:17], v[10:13]
	s_nop 4
	ds_read_b128 v[10:13], v1 offset:20736
	ds_read_b128 v[14:17], v1 offset:20800
	s_waitcnt lgkmcnt(1)
	v_mfma_f32_16x16x32_bf16 v[10:13], v[2:5], v[10:13], v[30:33]
	s_waitcnt lgkmcnt(0)
	v_mfma_f32_16x16x32_bf16 v[30:33], v[6:9], v[14:17], v[10:13]
	s_nop 5
	ds_read_b128 v[10:13], v1 offset:23040
	ds_read_b128 v[14:17], v1 offset:23104
	s_waitcnt lgkmcnt(1)
	v_mfma_f32_16x16x32_bf16 v[10:13], v[2:5], v[10:13], v[38:41]
	s_waitcnt lgkmcnt(0)
	v_mfma_f32_16x16x32_bf16 v[26:29], v[6:9], v[14:17], v[10:13]
	s_nop 5
	ds_read_b128 v[10:13], v1 offset:25344
	ds_read_b128 v[14:17], v1 offset:25408
	s_waitcnt lgkmcnt(1)
	v_mfma_f32_16x16x32_bf16 v[10:13], v[2:5], v[10:13], v[42:45]
	v_mfma_f32_16x16x32_bf16 v[58:61], v[22:25], v[62:65], v[18:21]
	v_lshl_add_u64 v[62:63], v[74:75], 0, v[120:121]
	s_waitcnt lgkmcnt(0)
	v_mfma_f32_16x16x32_bf16 v[22:25], v[6:9], v[14:17], v[10:13]
	s_nop 3
	ds_read_b128 v[10:13], v1 offset:27648
	ds_read_b128 v[14:17], v1 offset:27712
	s_waitcnt lgkmcnt(1)
	v_mfma_f32_16x16x32_bf16 v[10:13], v[2:5], v[10:13], v[46:49]
	s_nop 2
	v_lshl_add_u64 v[46:47], v[74:75], 0, v[116:117]
	s_waitcnt lgkmcnt(0)
	v_mfma_f32_16x16x32_bf16 v[18:21], v[6:9], v[14:17], v[10:13]
	s_nop 2
	ds_read_b128 v[10:13], v1 offset:29952
	ds_read_b128 v[14:17], v1 offset:30016
	s_waitcnt lgkmcnt(1)
	v_mfma_f32_16x16x32_bf16 v[10:13], v[2:5], v[10:13], v[50:53]
	s_waitcnt lgkmcnt(0)
	v_mfma_f32_16x16x32_bf16 v[14:17], v[6:9], v[14:17], v[10:13]
	s_nop 5
	ds_read_b128 v[10:13], v1 offset:32256
	ds_read_b128 v[38:41], v1 offset:32320
	s_waitcnt lgkmcnt(1)
	v_mfma_f32_16x16x32_bf16 v[10:13], v[2:5], v[10:13], v[54:57]
	s_nop 2
	v_lshl_add_u64 v[54:55], v[74:75], 0, v[118:119]
	s_waitcnt lgkmcnt(0)
	v_mfma_f32_16x16x32_bf16 v[10:13], v[6:9], v[38:41], v[10:13]
	ds_read_b128 v[38:41], v1 offset:34560
	ds_read_b128 v[42:45], v1 offset:34624
	s_waitcnt lgkmcnt(1)
	v_mfma_f32_16x16x32_bf16 v[2:5], v[2:5], v[38:41], v[58:61]
	v_mov_b64_e32 v[38:39], s[10:11]
	s_waitcnt lgkmcnt(0)
	v_mfma_f32_16x16x32_bf16 v[2:5], v[6:9], v[42:45], v[2:5]
	s_nop 0
	s_nop 0
	v_lshl_add_u64 v[42:43], v[74:75], 0, v[112:113]
	s_waitcnt vmcnt(0)
	v_mov_b32_e32 v6, v244
	v_mov_b32_e32 v7, v245
	v_mov_b32_e32 v8, v246
	v_mov_b32_e32 v9, v247
	v_pk_fma_f32 v[6:7], v[6:7], s[8:9], v[38:39] op_sel_hi:[1,0,0]
	s_nop 0
	v_mul_f32_e32 v40, 0x4b800000, v6
	v_cmp_gt_f32_e64 s[0:1], s20, v6
	v_cmp_gt_f32_e32 vcc, s20, v7
	s_nop 0
	v_cndmask_b32_e64 v6, v6, v40, s[0:1]
	v_rsq_f32_e32 v6, v6
	s_nop 0
	v_mul_f32_e32 v40, 0x45800000, v6
	v_cndmask_b32_e64 v40, v6, v40, s[0:1]
	v_mul_f32_e32 v6, 0x4b800000, v7
	v_cndmask_b32_e32 v6, v7, v6, vcc
	v_rsq_f32_e32 v6, v6
	v_mul_f32_e32 v2, v2, v40
	v_mul_f32_e32 v7, 0x45800000, v6
	v_cndmask_b32_e32 v41, v6, v7, vcc
	v_pk_fma_f32 v[6:7], v[8:9], s[8:9], v[38:39] op_sel_hi:[1,0,0]
	v_lshl_add_u64 v[38:39], v[74:75], 0, v[114:115]
	v_mul_f32_e32 v8, 0x4b800000, v6
	v_cmp_gt_f32_e64 s[0:1], s20, v6
	v_cmp_gt_f32_e32 vcc, s20, v7
	s_nop 0
	v_cndmask_b32_e64 v6, v6, v8, s[0:1]
	v_rsq_f32_e32 v6, v6
	s_nop 0
	v_mul_f32_e32 v8, 0x45800000, v6
	v_cndmask_b32_e64 v6, v6, v8, s[0:1]
	v_mul_f32_e32 v8, 0x4b800000, v7
	v_cndmask_b32_e32 v7, v7, v8, vcc
	v_rsq_f32_e32 v7, v7
	s_lshl_b64 s[0:1], s[12:13], 10
	s_add_u32 s0, s56, s0
	s_addc_u32 s1, s57, s1
	v_mul_f32_e32 v8, 0x45800000, v7
	v_cndmask_b32_e32 v7, v7, v8, vcc
	v_mul_f32_e32 v8, v34, v40
	v_cvt_pk_bf16_f32 v8, v8, v99
	ds_write_b16 v163, v8 offset:36864
	v_mul_f32_e32 v8, v35, v41
	v_cvt_pk_bf16_f32 v8, v8, v99
	ds_write_b16 v163, v8 offset:37136
	v_mul_f32_e32 v8, v36, v6
	v_cvt_pk_bf16_f32 v8, v8, v99
	ds_write_b16 v163, v8 offset:37408
	v_mul_f32_e32 v8, v37, v7
	v_cvt_pk_bf16_f32 v8, v8, v99
	ds_write_b16 v163, v8 offset:37680
	v_mul_f32_e32 v8, v30, v40
	v_cvt_pk_bf16_f32 v8, v8, v99
	ds_write_b16 v163, v8 offset:36896
	v_mul_f32_e32 v8, v31, v41
	v_cvt_pk_bf16_f32 v8, v8, v99
	ds_write_b16 v163, v8 offset:37168
	v_mul_f32_e32 v8, v32, v6
	v_cvt_pk_bf16_f32 v8, v8, v99
	ds_write_b16 v163, v8 offset:37440
	v_mul_f32_e32 v8, v33, v7
	v_cvt_pk_bf16_f32 v8, v8, v99
	ds_write_b16 v163, v8 offset:37712
	v_mul_f32_e32 v8, v26, v40
	v_cvt_pk_bf16_f32 v8, v8, v99
	ds_write_b16 v163, v8 offset:36928
	v_mul_f32_e32 v8, v27, v41
	v_cvt_pk_bf16_f32 v8, v8, v99
	ds_write_b16 v163, v8 offset:37200
	v_mul_f32_e32 v8, v28, v6
	v_cvt_pk_bf16_f32 v8, v8, v99
	ds_write_b16 v163, v8 offset:37472
	v_mul_f32_e32 v8, v29, v7
	v_cvt_pk_bf16_f32 v8, v8, v99
	ds_write_b16 v163, v8 offset:37744
	v_mul_f32_e32 v8, v22, v40
	v_cvt_pk_bf16_f32 v8, v8, v99
	ds_write_b16 v163, v8 offset:36960
	v_mul_f32_e32 v8, v23, v41
	v_cvt_pk_bf16_f32 v8, v8, v99
	ds_write_b16 v163, v8 offset:37232
	v_mul_f32_e32 v8, v24, v6
	v_cvt_pk_bf16_f32 v8, v8, v99
	ds_write_b16 v163, v8 offset:37504
	v_mul_f32_e32 v8, v25, v7
	v_cvt_pk_bf16_f32 v8, v8, v99
	ds_write_b16 v163, v8 offset:37776
	v_mul_f32_e32 v8, v18, v40
	v_cvt_pk_bf16_f32 v8, v8, v99
	ds_write_b16 v163, v8 offset:36992
	v_mul_f32_e32 v8, v19, v41
	v_cvt_pk_bf16_f32 v8, v8, v99
	ds_write_b16 v163, v8 offset:37264
	v_mul_f32_e32 v8, v20, v6
	v_cvt_pk_bf16_f32 v8, v8, v99
	ds_write_b16 v163, v8 offset:37536
	v_mul_f32_e32 v8, v21, v7
	v_cvt_pk_bf16_f32 v8, v8, v99
	ds_write_b16 v163, v8 offset:37808
	v_mul_f32_e32 v8, v14, v40
	v_cvt_pk_bf16_f32 v8, v8, v99
	ds_write_b16 v163, v8 offset:37024
	v_mul_f32_e32 v8, v15, v41
	v_cvt_pk_bf16_f32 v8, v8, v99
	ds_write_b16 v163, v8 offset:37296
	v_mul_f32_e32 v8, v16, v6
	v_cvt_pk_bf16_f32 v8, v8, v99
	ds_write_b16 v163, v8 offset:37568
	v_mul_f32_e32 v8, v17, v7
	v_cvt_pk_bf16_f32 v8, v8, v99
	ds_write_b16 v163, v8 offset:37840
	v_mul_f32_e32 v8, v10, v40
	v_cvt_pk_bf16_f32 v8, v8, v99
	ds_write_b16 v163, v8 offset:37056
	v_mul_f32_e32 v8, v11, v41
	v_cvt_pk_bf16_f32 v8, v8, v99
	ds_write_b16 v163, v8 offset:37328
	v_mul_f32_e32 v8, v12, v6
	v_cvt_pk_bf16_f32 v8, v8, v99
	ds_write_b16 v163, v8 offset:37600
	v_mul_f32_e32 v8, v13, v7
	v_cvt_pk_bf16_f32 v8, v8, v99
	ds_write_b16 v163, v8 offset:37872
	v_cvt_pk_bf16_f32 v2, v2, v99
	ds_write_b16 v163, v2 offset:37088
	v_mul_f32_e32 v2, v3, v41
	v_cvt_pk_bf16_f32 v2, v2, v99
	ds_write_b16 v163, v2 offset:37360
	v_mul_f32_e32 v2, v4, v6
	v_cvt_pk_bf16_f32 v2, v2, v99
	ds_write_b16 v163, v2 offset:37632
	v_mul_f32_e32 v2, v5, v7
	v_add_co_u32_e32 v38, vcc, s21, v38
	v_cvt_pk_bf16_f32 v2, v2, v99
	ds_write_b16 v163, v2 offset:37904
	s_nop 0
	v_addc_co_u32_e32 v39, vcc, -1, v39, vcc
	s_waitcnt lgkmcnt(0)
	s_barrier
	ds_read_b128 v[14:17], v164 offset:36864
	ds_read_b128 v[10:13], v164 offset:36928
	ds_read_b128 v[6:9], v164 offset:36992
	ds_read_b128 v[2:5], v164 offset:37056
	v_lshl_add_u64 v[18:19], v[74:75], 0, v[104:105]
	global_load_dwordx4 v[34:37], v[42:43], off
	v_lshl_add_u64 v[22:23], v[74:75], 0, v[106:107]
	global_load_dwordx4 v[38:41], v[38:39], off
	v_add_co_u32_e32 v42, vcc, s22, v42
	global_load_dwordx4 v[18:21], v[18:19], off
	v_lshl_add_u64 v[26:27], v[74:75], 0, v[108:109]
	v_lshl_add_u64 v[30:31], v[74:75], 0, v[110:111]
	v_addc_co_u32_e32 v43, vcc, 0, v43, vcc
	global_load_dwordx4 v[22:25], v[22:23], off
	v_add_co_u32_e32 v70, vcc, s23, v66
	global_load_dwordx4 v[26:29], v[26:27], off
	s_nop 0
	v_addc_co_u32_e32 v71, vcc, -1, v67, vcc
	global_load_dwordx4 v[30:33], v[30:31], off
	s_add_u32 s0, s0, s2
	global_load_dwordx4 v[42:45], v[42:43], off
	s_addc_u32 s1, s1, 0
	global_load_dwordx4 v[46:49], v[46:47], off
	s_nop 0
	global_load_dwordx4 v[50:53], v[54:55], off offset:1024
	s_nop 0
	global_load_dwordx4 v[54:57], v[54:55], off offset:3072
	s_nop 0
	global_load_dwordx4 v[58:61], v[62:63], off offset:1024
	s_nop 0
	global_load_dwordx4 v[62:65], v[62:63], off offset:3072
	s_nop 0
	global_load_dwordx4 v[66:69], v[70:71], off offset:-3072
	s_nop 0
	global_load_dwordx4 v[70:73], v[70:71], off offset:-1024
	s_nop 0
	global_load_dwordx4 v[74:77], v[78:79], off offset:1024
	s_nop 0
	global_load_dwordx4 v[78:81], v[78:79], off offset:3072
	s_waitcnt lgkmcnt(0)
	s_barrier
	s_waitcnt vmcnt(13)
	ds_write_b128 v166, v[18:21]
	s_waitcnt vmcnt(12)
	ds_write_b128 v167, v[22:25]
	s_waitcnt vmcnt(11)
	ds_write_b128 v168, v[26:29]
	s_waitcnt vmcnt(10)
	ds_write_b128 v169, v[30:33]
	ds_write_b128 v166, v[34:37] offset:34816
	ds_write_b128 v170, v[38:41]
	s_waitcnt vmcnt(9)
	ds_write_b128 v166, v[42:45] offset:52224
	s_waitcnt vmcnt(8)
	ds_write_b128 v171, v[46:49]
	v_add_u32_e32 v20, 0x400, v140
	s_add_i32 s27, s27, s88
	s_add_i32 s3, s3, s9
	s_add_i32 s11, s11, s16
	s_cmpk_lt_i32 s27, 0x100
	s_waitcnt vmcnt(7)
	v_and_b32_e32 v18, 0xffff, v50
	v_lshrrev_b32_e32 v19, 16, v50
	s_waitcnt vmcnt(6)
	v_lshl_or_b32 v18, v54, 16, v18
	v_and_or_b32 v19, v54, s24, v19
	ds_write2_b32 v140, v18, v19 offset1:132
	v_and_b32_e32 v18, 0xffff, v51
	v_lshrrev_b32_e32 v19, 16, v51
	v_lshl_or_b32 v18, v55, 16, v18
	v_and_or_b32 v19, v55, s24, v19
	ds_write2_b32 v20, v18, v19 offset0:8 offset1:140
	v_and_b32_e32 v18, 0xffff, v52
	v_lshrrev_b32_e32 v19, 16, v52
	v_lshl_or_b32 v18, v56, 16, v18
	v_and_or_b32 v19, v56, s24, v19
	v_add_u32_e32 v20, 0x800, v140
	ds_write2_b32 v20, v18, v19 offset0:16 offset1:148
	v_and_b32_e32 v18, 0xffff, v53
	v_lshrrev_b32_e32 v19, 16, v53
	v_lshl_or_b32 v18, v57, 16, v18
	v_and_or_b32 v19, v57, s24, v19
	v_add_u32_e32 v20, 0xc00, v140
	ds_write2_b32 v20, v18, v19 offset0:24 offset1:156
	s_waitcnt vmcnt(5)
	v_and_b32_e32 v18, 0xffff, v58
	v_lshrrev_b32_e32 v19, 16, v58
	s_waitcnt vmcnt(4)
	v_lshl_or_b32 v18, v62, 16, v18
	v_and_or_b32 v19, v62, s24, v19
	ds_write2_b32 v141, v18, v19 offset1:132
	v_and_b32_e32 v18, 0xffff, v59
	v_lshrrev_b32_e32 v19, 16, v59
	v_lshl_or_b32 v18, v63, 16, v18
	v_and_or_b32 v19, v63, s24, v19
	v_add_u32_e32 v20, 0x400, v141
	ds_write2_b32 v20, v18, v19 offset0:8 offset1:140
	v_and_b32_e32 v18, 0xffff, v60
	v_lshrrev_b32_e32 v19, 16, v60
	v_lshl_or_b32 v18, v64, 16, v18
	v_and_or_b32 v19, v64, s24, v19
	v_add_u32_e32 v20, 0x800, v141
	ds_write2_b32 v20, v18, v19 offset0:16 offset1:148
	v_and_b32_e32 v18, 0xffff, v61
	v_lshrrev_b32_e32 v19, 16, v61
	v_lshl_or_b32 v18, v65, 16, v18
	v_and_or_b32 v19, v65, s24, v19
	v_add_u32_e32 v20, 0xc00, v141
	ds_write2_b32 v20, v18, v19 offset0:24 offset1:156
	s_waitcnt vmcnt(3)
	v_and_b32_e32 v18, 0xffff, v66
	v_lshrrev_b32_e32 v19, 16, v66
	s_waitcnt vmcnt(2)
	v_lshl_or_b32 v18, v70, 16, v18
	v_and_or_b32 v19, v70, s24, v19
	ds_write2_b32 v142, v18, v19 offset1:132
	v_and_b32_e32 v18, 0xffff, v67
	v_lshrrev_b32_e32 v19, 16, v67
	v_lshl_or_b32 v18, v71, 16, v18
	v_and_or_b32 v19, v71, s24, v19
	v_add_u32_e32 v20, 0x400, v142
	ds_write2_b32 v20, v18, v19 offset0:8 offset1:140
	v_and_b32_e32 v18, 0xffff, v68
	v_lshrrev_b32_e32 v19, 16, v68
	v_lshl_or_b32 v18, v72, 16, v18
	v_and_or_b32 v19, v72, s24, v19
	v_add_u32_e32 v20, 0x800, v142
	ds_write2_b32 v20, v18, v19 offset0:16 offset1:148
	v_and_b32_e32 v18, 0xffff, v69
	v_lshrrev_b32_e32 v19, 16, v69
	v_lshl_or_b32 v18, v73, 16, v18
	v_and_or_b32 v19, v73, s24, v19
	v_add_u32_e32 v20, 0xc00, v142
	ds_write2_b32 v20, v18, v19 offset0:24 offset1:156
	s_waitcnt vmcnt(1)
	v_and_b32_e32 v18, 0xffff, v74
	v_lshrrev_b32_e32 v19, 16, v74
	s_waitcnt vmcnt(0)
	v_lshl_or_b32 v18, v78, 16, v18
	v_and_or_b32 v19, v78, s24, v19
	ds_write2_b32 v143, v18, v19 offset1:132
	v_and_b32_e32 v18, 0xffff, v75
	v_lshrrev_b32_e32 v19, 16, v75
	v_lshl_or_b32 v18, v79, 16, v18
	v_and_or_b32 v19, v79, s24, v19
	v_add_u32_e32 v20, 0x400, v143
	ds_write2_b32 v20, v18, v19 offset0:8 offset1:140
	v_and_b32_e32 v18, 0xffff, v76
	v_lshrrev_b32_e32 v19, 16, v76
	v_lshl_or_b32 v18, v80, 16, v18
	v_and_or_b32 v19, v80, s24, v19
	v_add_u32_e32 v20, 0x800, v143
	ds_write2_b32 v20, v18, v19 offset0:16 offset1:148
	v_and_b32_e32 v18, 0xffff, v77
	v_lshrrev_b32_e32 v19, 16, v77
	v_lshl_or_b32 v18, v81, 16, v18
	v_and_or_b32 v19, v81, s24, v19
	v_add_u32_e32 v20, 0xc00, v143
	ds_write2_b32 v20, v18, v19 offset0:24 offset1:156
	s_waitcnt lgkmcnt(0)
	s_barrier
	ds_read_b128 v[18:21], v172
	ds_read_b128 v[22:25], v172 offset:64
	s_waitcnt lgkmcnt(1)
	v_mfma_f32_16x16x32_bf16 v[18:21], v[18:21], v[14:17], 0
	ds_read_b128 v[26:29], v172 offset:4416
	s_waitcnt lgkmcnt(1)
	v_mfma_f32_16x16x32_bf16 v[18:21], v[22:25], v[10:13], v[18:21]
	ds_read_b128 v[22:25], v172 offset:128
	s_waitcnt lgkmcnt(0)
	v_mfma_f32_16x16x32_bf16 v[18:21], v[22:25], v[6:9], v[18:21]
	ds_read_b128 v[22:25], v172 offset:192
	s_waitcnt lgkmcnt(0)
	v_mfma_f32_16x16x32_bf16 v[18:21], v[22:25], v[2:5], v[18:21]
	s_nop 7
	v_mul_f32_e32 v22, 0x3db504f3, v18
	v_mul_f32_e32 v23, 0x3db504f3, v19
	v_max3_f32 v22, v22, s26, v23
	v_mul_f32_e32 v23, 0x3db504f3, v20
	v_mul_f32_e32 v24, 0x3db504f3, v21
	v_max3_f32 v30, v22, v23, v24
	ds_read_b128 v[22:25], v172 offset:4352
	s_waitcnt lgkmcnt(0)
	v_mfma_f32_16x16x32_bf16 v[22:25], v[22:25], v[14:17], 0
	v_mfma_f32_16x16x32_bf16 v[22:25], v[26:29], v[10:13], v[22:25]
	ds_read_b128 v[26:29], v172 offset:4480
	s_waitcnt lgkmcnt(0)
	v_mfma_f32_16x16x32_bf16 v[22:25], v[26:29], v[6:9], v[22:25]
	ds_read_b128 v[26:29], v172 offset:4544
	s_waitcnt lgkmcnt(0)
	v_mfma_f32_16x16x32_bf16 v[22:25], v[26:29], v[2:5], v[22:25]
	s_nop 7
	v_mul_f32_e32 v26, 0x3db504f3, v22
	v_mul_f32_e32 v27, 0x3db504f3, v23
	v_max3_f32 v26, v30, v26, v27
	v_mul_f32_e32 v27, 0x3db504f3, v24
	v_mul_f32_e32 v28, 0x3db504f3, v25
	v_max3_f32 v34, v26, v27, v28
	ds_read_b128 v[26:29], v172 offset:8704
	ds_read_b128 v[30:33], v172 offset:8768
	s_waitcnt lgkmcnt(1)
	v_mfma_f32_16x16x32_bf16 v[26:29], v[26:29], v[14:17], 0
	s_waitcnt lgkmcnt(0)
	v_mfma_f32_16x16x32_bf16 v[26:29], v[30:33], v[10:13], v[26:29]
	ds_read_b128 v[30:33], v172 offset:8832
	s_waitcnt lgkmcnt(0)
	v_mfma_f32_16x16x32_bf16 v[26:29], v[30:33], v[6:9], v[26:29]
	ds_read_b128 v[30:33], v172 offset:8896
	s_waitcnt lgkmcnt(0)
	v_mfma_f32_16x16x32_bf16 v[26:29], v[30:33], v[2:5], v[26:29]
	s_nop 7
	v_mul_f32_e32 v30, 0x3db504f3, v26
	v_mul_f32_e32 v31, 0x3db504f3, v27
	v_max3_f32 v30, v34, v30, v31
	v_mul_f32_e32 v31, 0x3db504f3, v28
	v_mul_f32_e32 v32, 0x3db504f3, v29
	v_max3_f32 v38, v30, v31, v32
	ds_read_b128 v[30:33], v172 offset:13056
	ds_read_b128 v[34:37], v172 offset:13120
	s_waitcnt lgkmcnt(1)
	v_mfma_f32_16x16x32_bf16 v[30:33], v[30:33], v[14:17], 0
	s_waitcnt lgkmcnt(0)
	v_mfma_f32_16x16x32_bf16 v[30:33], v[34:37], v[10:13], v[30:33]
	ds_read_b128 v[34:37], v172 offset:13184
	s_waitcnt lgkmcnt(0)
	v_mfma_f32_16x16x32_bf16 v[30:33], v[34:37], v[6:9], v[30:33]
	ds_read_b128 v[34:37], v172 offset:13248
	s_waitcnt lgkmcnt(0)
	v_mfma_f32_16x16x32_bf16 v[30:33], v[34:37], v[2:5], v[30:33]
	s_nop 7
	v_mul_f32_e32 v34, 0x3db504f3, v30
	v_mul_f32_e32 v35, 0x3db504f3, v31
	v_max3_f32 v34, v38, v34, v35
	v_mul_f32_e32 v35, 0x3db504f3, v32
	v_mul_f32_e32 v36, 0x3db504f3, v33
	v_max3_f32 v42, v34, v35, v36
	ds_read_b128 v[34:37], v172 offset:17408
	ds_read_b128 v[38:41], v172 offset:17472
	s_waitcnt lgkmcnt(1)
	v_mfma_f32_16x16x32_bf16 v[34:37], v[34:37], v[14:17], 0
	s_waitcnt lgkmcnt(0)
	v_mfma_f32_16x16x32_bf16 v[34:37], v[38:41], v[10:13], v[34:37]
	ds_read_b128 v[38:41], v172 offset:17536
	s_waitcnt lgkmcnt(0)
	v_mfma_f32_16x16x32_bf16 v[34:37], v[38:41], v[6:9], v[34:37]
	ds_read_b128 v[38:41], v172 offset:17600
	s_waitcnt lgkmcnt(0)
	v_mfma_f32_16x16x32_bf16 v[34:37], v[38:41], v[2:5], v[34:37]
	s_nop 7
	v_mul_f32_e32 v38, 0x3db504f3, v34
	v_mul_f32_e32 v39, 0x3db504f3, v35
	v_max3_f32 v38, v42, v38, v39
	v_mul_f32_e32 v39, 0x3db504f3, v36
	v_mul_f32_e32 v40, 0x3db504f3, v37
	v_max3_f32 v46, v38, v39, v40
	ds_read_b128 v[38:41], v172 offset:21760
	ds_read_b128 v[42:45], v172 offset:21824
	s_waitcnt lgkmcnt(1)
	v_mfma_f32_16x16x32_bf16 v[38:41], v[38:41], v[14:17], 0
	s_waitcnt lgkmcnt(0)
	v_mfma_f32_16x16x32_bf16 v[38:41], v[42:45], v[10:13], v[38:41]
	ds_read_b128 v[42:45], v172 offset:21888
	s_waitcnt lgkmcnt(0)
	v_mfma_f32_16x16x32_bf16 v[38:41], v[42:45], v[6:9], v[38:41]
	ds_read_b128 v[42:45], v172 offset:21952
	s_waitcnt lgkmcnt(0)
	v_mfma_f32_16x16x32_bf16 v[38:41], v[42:45], v[2:5], v[38:41]
	s_nop 7
	v_mul_f32_e32 v42, 0x3db504f3, v38
	v_mul_f32_e32 v43, 0x3db504f3, v39
	v_max3_f32 v42, v46, v42, v43
	v_mul_f32_e32 v43, 0x3db504f3, v40
	v_mul_f32_e32 v44, 0x3db504f3, v41
	v_max3_f32 v50, v42, v43, v44
	ds_read_b128 v[42:45], v172 offset:26112
	ds_read_b128 v[46:49], v172 offset:26176
	s_waitcnt lgkmcnt(1)
	v_mfma_f32_16x16x32_bf16 v[42:45], v[42:45], v[14:17], 0
	s_waitcnt lgkmcnt(0)
	v_mfma_f32_16x16x32_bf16 v[42:45], v[46:49], v[10:13], v[42:45]
	ds_read_b128 v[46:49], v172 offset:26240
	s_waitcnt lgkmcnt(0)
	v_mfma_f32_16x16x32_bf16 v[42:45], v[46:49], v[6:9], v[42:45]
	ds_read_b128 v[46:49], v172 offset:26304
	s_waitcnt lgkmcnt(0)
	v_mfma_f32_16x16x32_bf16 v[42:45], v[46:49], v[2:5], v[42:45]
	s_nop 7
	v_mul_f32_e32 v46, 0x3db504f3, v42
	v_mul_f32_e32 v47, 0x3db504f3, v43
	v_max3_f32 v46, v50, v46, v47
	v_mul_f32_e32 v47, 0x3db504f3, v44
	v_mul_f32_e32 v48, 0x3db504f3, v45
	v_max3_f32 v54, v46, v47, v48
	ds_read_b128 v[46:49], v172 offset:30464
	ds_read_b128 v[50:53], v172 offset:30528
	s_waitcnt lgkmcnt(1)
	v_mfma_f32_16x16x32_bf16 v[46:49], v[46:49], v[14:17], 0
	s_waitcnt lgkmcnt(0)
	v_mfma_f32_16x16x32_bf16 v[46:49], v[50:53], v[10:13], v[46:49]
	ds_read_b128 v[50:53], v172 offset:30592
	s_waitcnt lgkmcnt(0)
	v_mfma_f32_16x16x32_bf16 v[46:49], v[50:53], v[6:9], v[46:49]
	ds_read_b128 v[50:53], v172 offset:30656
	s_waitcnt lgkmcnt(0)
	v_mfma_f32_16x16x32_bf16 v[46:49], v[50:53], v[2:5], v[46:49]
	s_nop 7
	v_mul_f32_e32 v50, 0x3db504f3, v46
	v_mul_f32_e32 v51, 0x3db504f3, v47
	v_max3_f32 v50, v54, v50, v51
	v_mul_f32_e32 v51, 0x3db504f3, v48
	v_mul_f32_e32 v52, 0x3db504f3, v49
	v_max3_f32 v58, v50, v51, v52
	ds_read_b128 v[50:53], v172 offset:34816
	ds_read_b128 v[54:57], v172 offset:34880
	s_waitcnt lgkmcnt(1)
	v_mfma_f32_16x16x32_bf16 v[50:53], v[50:53], v[14:17], 0
	s_waitcnt lgkmcnt(0)
	v_mfma_f32_16x16x32_bf16 v[50:53], v[54:57], v[10:13], v[50:53]
	ds_read_b128 v[54:57], v172 offset:34944
	s_waitcnt lgkmcnt(0)
	v_mfma_f32_16x16x32_bf16 v[50:53], v[54:57], v[6:9], v[50:53]
	ds_read_b128 v[54:57], v172 offset:35008
	s_waitcnt lgkmcnt(0)
	v_mfma_f32_16x16x32_bf16 v[50:53], v[54:57], v[2:5], v[50:53]
	s_nop 7
	v_mul_f32_e32 v54, 0x3db504f3, v50
	v_mul_f32_e32 v55, 0x3db504f3, v51
	v_max3_f32 v54, v58, v54, v55
	v_mul_f32_e32 v55, 0x3db504f3, v52
	v_mul_f32_e32 v56, 0x3db504f3, v53
	v_max3_f32 v62, v54, v55, v56
	ds_read_b128 v[54:57], v172 offset:39168
	ds_read_b128 v[58:61], v172 offset:39232
	s_waitcnt lgkmcnt(1)
	v_mfma_f32_16x16x32_bf16 v[54:57], v[54:57], v[14:17], 0
	s_waitcnt lgkmcnt(0)
	v_mfma_f32_16x16x32_bf16 v[54:57], v[58:61], v[10:13], v[54:57]
	ds_read_b128 v[58:61], v172 offset:39296
	s_waitcnt lgkmcnt(0)
	v_mfma_f32_16x16x32_bf16 v[54:57], v[58:61], v[6:9], v[54:57]
	ds_read_b128 v[58:61], v172 offset:39360
	s_waitcnt lgkmcnt(0)
	v_mfma_f32_16x16x32_bf16 v[54:57], v[58:61], v[2:5], v[54:57]
	s_nop 7
	v_mul_f32_e32 v58, 0x3db504f3, v54
	v_mul_f32_e32 v59, 0x3db504f3, v55
	v_max3_f32 v58, v62, v58, v59
	v_mul_f32_e32 v59, 0x3db504f3, v56
	v_mul_f32_e32 v60, 0x3db504f3, v57
	v_max3_f32 v66, v58, v59, v60
	ds_read_b128 v[58:61], v172 offset:43520
	ds_read_b128 v[62:65], v172 offset:43584
	s_waitcnt lgkmcnt(1)
	v_mfma_f32_16x16x32_bf16 v[58:61], v[58:61], v[14:17], 0
	s_waitcnt lgkmcnt(0)
	v_mfma_f32_16x16x32_bf16 v[58:61], v[62:65], v[10:13], v[58:61]
	ds_read_b128 v[62:65], v172 offset:43648
	s_waitcnt lgkmcnt(0)
	v_mfma_f32_16x16x32_bf16 v[58:61], v[62:65], v[6:9], v[58:61]
	ds_read_b128 v[62:65], v172 offset:43712
	s_waitcnt lgkmcnt(0)
	v_mfma_f32_16x16x32_bf16 v[58:61], v[62:65], v[2:5], v[58:61]
	s_nop 7
	v_mul_f32_e32 v62, 0x3db504f3, v58
	v_mul_f32_e32 v63, 0x3db504f3, v59
	v_max3_f32 v62, v66, v62, v63
	v_mul_f32_e32 v63, 0x3db504f3, v60
	v_mul_f32_e32 v64, 0x3db504f3, v61
	v_max3_f32 v70, v62, v63, v64
	ds_read_b128 v[62:65], v172 offset:47872
	ds_read_b128 v[66:69], v172 offset:47936
	s_waitcnt lgkmcnt(1)
	v_mfma_f32_16x16x32_bf16 v[62:65], v[62:65], v[14:17], 0
	s_waitcnt lgkmcnt(0)
	v_mfma_f32_16x16x32_bf16 v[62:65], v[66:69], v[10:13], v[62:65]
	ds_read_b128 v[66:69], v172 offset:48000
	s_waitcnt lgkmcnt(0)
	v_mfma_f32_16x16x32_bf16 v[62:65], v[66:69], v[6:9], v[62:65]
	ds_read_b128 v[66:69], v172 offset:48064
	s_waitcnt lgkmcnt(0)
	v_mfma_f32_16x16x32_bf16 v[62:65], v[66:69], v[2:5], v[62:65]
	s_nop 7
	v_mul_f32_e32 v66, 0x3db504f3, v62
	v_mul_f32_e32 v67, 0x3db504f3, v63
	v_max3_f32 v66, v70, v66, v67
	v_mul_f32_e32 v67, 0x3db504f3, v64
	v_mul_f32_e32 v68, 0x3db504f3, v65
	v_max3_f32 v74, v66, v67, v68
	ds_read_b128 v[66:69], v172 offset:52224
	ds_read_b128 v[70:73], v172 offset:52288
	s_waitcnt lgkmcnt(1)
	v_mfma_f32_16x16x32_bf16 v[66:69], v[66:69], v[14:17], 0
	s_waitcnt lgkmcnt(0)
	v_mfma_f32_16x16x32_bf16 v[66:69], v[70:73], v[10:13], v[66:69]
	ds_read_b128 v[70:73], v172 offset:52352
	s_waitcnt lgkmcnt(0)
	v_mfma_f32_16x16x32_bf16 v[66:69], v[70:73], v[6:9], v[66:69]
	ds_read_b128 v[70:73], v172 offset:52416
	s_waitcnt lgkmcnt(0)
	v_mfma_f32_16x16x32_bf16 v[66:69], v[70:73], v[2:5], v[66:69]
	s_nop 7
	v_mul_f32_e32 v70, 0x3db504f3, v66
	v_mul_f32_e32 v71, 0x3db504f3, v67
	v_max3_f32 v70, v74, v70, v71
	v_mul_f32_e32 v71, 0x3db504f3, v68
	v_mul_f32_e32 v72, 0x3db504f3, v69
	v_max3_f32 v78, v70, v71, v72
	ds_read_b128 v[70:73], v172 offset:56576
	ds_read_b128 v[74:77], v172 offset:56640
	s_waitcnt lgkmcnt(1)
	v_mfma_f32_16x16x32_bf16 v[70:73], v[70:73], v[14:17], 0
	s_waitcnt lgkmcnt(0)
	v_mfma_f32_16x16x32_bf16 v[70:73], v[74:77], v[10:13], v[70:73]
	ds_read_b128 v[74:77], v172 offset:56704
	s_waitcnt lgkmcnt(0)
	v_mfma_f32_16x16x32_bf16 v[70:73], v[74:77], v[6:9], v[70:73]
	ds_read_b128 v[74:77], v172 offset:56768
	s_waitcnt lgkmcnt(0)
	v_mfma_f32_16x16x32_bf16 v[70:73], v[74:77], v[2:5], v[70:73]
	s_nop 7
	v_mul_f32_e32 v74, 0x3db504f3, v70
	v_mul_f32_e32 v75, 0x3db504f3, v71
	v_max3_f32 v74, v78, v74, v75
	v_mul_f32_e32 v75, 0x3db504f3, v72
	v_mul_f32_e32 v76, 0x3db504f3, v73
	v_max3_f32 v82, v74, v75, v76
	ds_read_b128 v[74:77], v172 offset:60928
	ds_read_b128 v[78:81], v172 offset:60992
	s_waitcnt lgkmcnt(1)
	v_mfma_f32_16x16x32_bf16 v[74:77], v[74:77], v[14:17], 0
	s_waitcnt lgkmcnt(0)
	v_mfma_f32_16x16x32_bf16 v[74:77], v[78:81], v[10:13], v[74:77]
	ds_read_b128 v[78:81], v172 offset:61056
	s_waitcnt lgkmcnt(0)
	v_mfma_f32_16x16x32_bf16 v[74:77], v[78:81], v[6:9], v[74:77]
	ds_read_b128 v[78:81], v172 offset:61120
	s_waitcnt lgkmcnt(0)
	v_mfma_f32_16x16x32_bf16 v[74:77], v[78:81], v[2:5], v[74:77]
	s_nop 7
	v_mul_f32_e32 v78, 0x3db504f3, v74
	v_mul_f32_e32 v79, 0x3db504f3, v75
	v_max3_f32 v78, v82, v78, v79
	v_mul_f32_e32 v79, 0x3db504f3, v76
	v_mul_f32_e32 v80, 0x3db504f3, v77
	v_max3_f32 v82, v78, v79, v80
	ds_read_b128 v[78:81], v172 offset:65280
	s_waitcnt lgkmcnt(0)
	v_mfma_f32_16x16x32_bf16 v[14:17], v[78:81], v[14:17], 0
	ds_read_b128 v[78:81], v172 offset:65344
	s_waitcnt lgkmcnt(0)
	v_mfma_f32_16x16x32_bf16 v[10:13], v[78:81], v[10:13], v[14:17]
	s_nop 4
	ds_read_b128 v[14:17], v172 offset:65408
	s_waitcnt lgkmcnt(0)
	v_mfma_f32_16x16x32_bf16 v[6:9], v[14:17], v[6:9], v[10:13]
	s_nop 2
	ds_read_b128 v[10:13], v172 offset:65472
	s_waitcnt lgkmcnt(0)
	v_mfma_f32_16x16x32_bf16 v[2:5], v[10:13], v[2:5], v[6:9]
	s_nop 7
	v_mul_f32_e32 v6, 0x3db504f3, v2
	v_mul_f32_e32 v7, 0x3db504f3, v3
	v_max3_f32 v6, v82, v6, v7
	v_mul_f32_e32 v7, 0x3db504f3, v4
	v_mul_f32_e32 v8, 0x3db504f3, v5
	v_max3_f32 v6, v6, v7, v8
	v_and_b32_e32 v8, 64, v174
	v_xor_b32_e32 v7, 16, v174
	v_add_u32_e32 v8, 64, v8
	v_cmp_lt_i32_e32 vcc, v7, v8
	s_nop 1
	v_cndmask_b32_e32 v7, v174, v7, vcc
	v_lshlrev_b32_e32 v138, 2, v7
	ds_bpermute_b32 v7, v138, v6
	s_waitcnt lgkmcnt(0)
	v_max_f32_e32 v7, v7, v7
	v_max_f32_e32 v6, v6, v7
	v_xor_b32_e32 v7, 32, v174
	v_cmp_lt_i32_e32 vcc, v7, v8
	s_nop 1
	v_cndmask_b32_e32 v7, v174, v7, vcc
	v_lshlrev_b32_e32 v139, 2, v7
	ds_bpermute_b32 v7, v139, v6
	s_waitcnt lgkmcnt(0)
	v_max_f32_e32 v7, v7, v7
	v_max_f32_e32 v175, v6, v7
	v_fma_f32 v7, v19, s25, -v175
	v_mul_f32_e32 v7, 0x3fb8aa3b, v7
	v_exp_f32_e32 v95, v7
	v_fma_f32 v7, v20, s25, -v175
	v_mul_f32_e32 v7, 0x3fb8aa3b, v7
	v_exp_f32_e32 v96, v7
	v_fma_f32 v7, v21, s25, -v175
	v_mul_f32_e32 v7, 0x3fb8aa3b, v7
	v_exp_f32_e32 v97, v7
	v_fma_f32 v7, v22, s25, -v175
	v_mul_f32_e32 v7, 0x3fb8aa3b, v7
	v_exp_f32_e32 v133, v7
	v_fma_f32 v7, v23, s25, -v175
	v_mul_f32_e32 v7, 0x3fb8aa3b, v7
	v_exp_f32_e32 v135, v7
	v_fma_f32 v7, v24, s25, -v175
	v_mul_f32_e32 v7, 0x3fb8aa3b, v7
	v_exp_f32_e32 v136, v7
	v_fma_f32 v7, v25, s25, -v175
	v_mul_f32_e32 v7, 0x3fb8aa3b, v7
	v_exp_f32_e32 v137, v7
	v_fma_f32 v7, v26, s25, -v175
	v_mul_f32_e32 v7, 0x3fb8aa3b, v7
	v_exp_f32_e32 v86, v7
	v_fma_f32 v7, v27, s25, -v175
	v_mul_f32_e32 v7, 0x3fb8aa3b, v7
	v_exp_f32_e32 v87, v7
	v_fma_f32 v7, v28, s25, -v175
	v_mul_f32_e32 v7, 0x3fb8aa3b, v7
	v_exp_f32_e32 v88, v7
	v_fma_f32 v7, v29, s25, -v175
	v_mul_f32_e32 v7, 0x3fb8aa3b, v7
	v_exp_f32_e32 v89, v7
	v_fma_f32 v7, v30, s25, -v175
	v_mul_f32_e32 v7, 0x3fb8aa3b, v7
	v_exp_f32_e32 v90, v7
	v_fma_f32 v7, v31, s25, -v175
	v_mul_f32_e32 v7, 0x3fb8aa3b, v7
	v_exp_f32_e32 v91, v7
	v_fma_f32 v7, v32, s25, -v175
	v_mul_f32_e32 v7, 0x3fb8aa3b, v7
	v_exp_f32_e32 v92, v7
	v_fma_f32 v7, v33, s25, -v175
	v_mul_f32_e32 v7, 0x3fb8aa3b, v7
	v_exp_f32_e32 v93, v7
	v_fma_f32 v7, v34, s25, -v175
	v_mul_f32_e32 v7, 0x3fb8aa3b, v7
	v_exp_f32_e32 v78, v7
	v_fma_f32 v7, v35, s25, -v175
	v_mul_f32_e32 v7, 0x3fb8aa3b, v7
	v_exp_f32_e32 v79, v7
	v_fma_f32 v7, v36, s25, -v175
	v_mul_f32_e32 v7, 0x3fb8aa3b, v7
	v_exp_f32_e32 v80, v7
	v_fma_f32 v7, v37, s25, -v175
	v_mul_f32_e32 v7, 0x3fb8aa3b, v7
	v_exp_f32_e32 v81, v7
	v_fma_f32 v7, v38, s25, -v175
	v_mul_f32_e32 v7, 0x3fb8aa3b, v7
	v_exp_f32_e32 v82, v7
	v_fma_f32 v7, v39, s25, -v175
	v_mul_f32_e32 v7, 0x3fb8aa3b, v7
	v_exp_f32_e32 v83, v7
	v_fma_f32 v7, v40, s25, -v175
	v_mul_f32_e32 v7, 0x3fb8aa3b, v7
	v_exp_f32_e32 v84, v7
	v_fma_f32 v7, v41, s25, -v175
	v_mul_f32_e32 v7, 0x3fb8aa3b, v7
	v_exp_f32_e32 v85, v7
	v_fma_f32 v7, v42, s25, -v175
	v_mul_f32_e32 v7, 0x3fb8aa3b, v7
	v_exp_f32_e32 v36, v7
	v_fma_f32 v7, v43, s25, -v175
	v_mul_f32_e32 v7, 0x3fb8aa3b, v7
	v_exp_f32_e32 v37, v7
	v_fma_f32 v7, v44, s25, -v175
	v_mul_f32_e32 v7, 0x3fb8aa3b, v7
	v_exp_f32_e32 v38, v7
	v_fma_f32 v7, v45, s25, -v175
	v_fma_f32 v6, v18, s25, -v175
	v_mul_f32_e32 v7, 0x3fb8aa3b, v7
	v_mul_f32_e32 v6, 0x3fb8aa3b, v6
	v_exp_f32_e32 v39, v7
	v_fma_f32 v7, v46, s25, -v175
	v_exp_f32_e32 v94, v6
	v_mul_f32_e32 v7, 0x3fb8aa3b, v7
	v_exp_f32_e32 v40, v7
	v_fma_f32 v7, v47, s25, -v175
	v_mul_f32_e32 v7, 0x3fb8aa3b, v7
	v_exp_f32_e32 v41, v7
	v_fma_f32 v7, v48, s25, -v175
	v_add_f32_e32 v6, 0, v94
	v_mul_f32_e32 v7, 0x3fb8aa3b, v7
	v_add_f32_e32 v6, v95, v6
	v_exp_f32_e32 v42, v7
	v_fma_f32 v7, v49, s25, -v175
	v_add_f32_e32 v6, v96, v6
	v_mul_f32_e32 v7, 0x3fb8aa3b, v7
	v_add_f32_e32 v6, v97, v6
	v_exp_f32_e32 v43, v7
	v_fma_f32 v7, v50, s25, -v175
	v_add_f32_e32 v6, v133, v6
	v_mul_f32_e32 v7, 0x3fb8aa3b, v7
	v_add_f32_e32 v6, v135, v6
	v_exp_f32_e32 v28, v7
	v_fma_f32 v7, v51, s25, -v175
	v_add_f32_e32 v6, v136, v6
	v_mul_f32_e32 v7, 0x3fb8aa3b, v7
	v_add_f32_e32 v6, v137, v6
	v_exp_f32_e32 v29, v7
	v_fma_f32 v7, v52, s25, -v175
	v_add_f32_e32 v6, v86, v6
	v_mul_f32_e32 v7, 0x3fb8aa3b, v7
	v_add_f32_e32 v6, v87, v6
	v_exp_f32_e32 v30, v7
	v_fma_f32 v7, v53, s25, -v175
	v_add_f32_e32 v6, v88, v6
	v_mul_f32_e32 v7, 0x3fb8aa3b, v7
	v_add_f32_e32 v6, v89, v6
	v_exp_f32_e32 v31, v7
	v_fma_f32 v7, v54, s25, -v175
	v_add_f32_e32 v6, v90, v6
	v_mul_f32_e32 v7, 0x3fb8aa3b, v7
	v_add_f32_e32 v6, v91, v6
	v_exp_f32_e32 v32, v7
	v_fma_f32 v7, v55, s25, -v175
	v_add_f32_e32 v6, v92, v6
	v_mul_f32_e32 v7, 0x3fb8aa3b, v7
	v_add_f32_e32 v6, v93, v6
	v_exp_f32_e32 v33, v7
	v_fma_f32 v7, v56, s25, -v175
	v_add_f32_e32 v6, v78, v6
	v_mul_f32_e32 v7, 0x3fb8aa3b, v7
	v_add_f32_e32 v6, v79, v6
	v_exp_f32_e32 v34, v7
	v_fma_f32 v7, v57, s25, -v175
	v_add_f32_e32 v6, v80, v6
	v_mul_f32_e32 v7, 0x3fb8aa3b, v7
	v_add_f32_e32 v6, v81, v6
	v_exp_f32_e32 v35, v7
	v_fma_f32 v7, v58, s25, -v175
	v_add_f32_e32 v6, v82, v6
	v_mul_f32_e32 v7, 0x3fb8aa3b, v7
	v_add_f32_e32 v6, v83, v6
	v_exp_f32_e32 v20, v7
	v_fma_f32 v7, v59, s25, -v175
	v_add_f32_e32 v6, v84, v6
	v_mul_f32_e32 v7, 0x3fb8aa3b, v7
	v_add_f32_e32 v6, v85, v6
	v_exp_f32_e32 v21, v7
	v_fma_f32 v7, v60, s25, -v175
	v_add_f32_e32 v6, v36, v6
	v_mul_f32_e32 v7, 0x3fb8aa3b, v7
	v_add_f32_e32 v6, v37, v6
	v_exp_f32_e32 v22, v7
	v_fma_f32 v7, v61, s25, -v175
	v_add_f32_e32 v6, v38, v6
	v_mul_f32_e32 v7, 0x3fb8aa3b, v7
	v_add_f32_e32 v6, v39, v6
	v_exp_f32_e32 v23, v7
	v_fma_f32 v7, v62, s25, -v175
	v_add_f32_e32 v6, v40, v6
	v_mul_f32_e32 v7, 0x3fb8aa3b, v7
	v_add_f32_e32 v6, v41, v6
	v_exp_f32_e32 v24, v7
	v_fma_f32 v7, v63, s25, -v175
	v_add_f32_e32 v6, v42, v6
	v_mul_f32_e32 v7, 0x3fb8aa3b, v7
	v_add_f32_e32 v6, v43, v6
	v_exp_f32_e32 v25, v7
	v_fma_f32 v7, v64, s25, -v175
	v_add_f32_e32 v6, v28, v6
	v_mul_f32_e32 v7, 0x3fb8aa3b, v7
	v_add_f32_e32 v6, v29, v6
	v_exp_f32_e32 v26, v7
	v_fma_f32 v7, v65, s25, -v175
	v_add_f32_e32 v6, v30, v6
	v_mul_f32_e32 v7, 0x3fb8aa3b, v7
	v_add_f32_e32 v6, v31, v6
	v_exp_f32_e32 v27, v7
	v_fma_f32 v7, v66, s25, -v175
	v_add_f32_e32 v6, v32, v6
	v_mul_f32_e32 v7, 0x3fb8aa3b, v7
	v_add_f32_e32 v6, v33, v6
	v_exp_f32_e32 v12, v7
	v_fma_f32 v7, v67, s25, -v175
	v_add_f32_e32 v6, v34, v6
	v_mul_f32_e32 v7, 0x3fb8aa3b, v7
	v_add_f32_e32 v6, v35, v6
	v_exp_f32_e32 v13, v7
	v_fma_f32 v7, v68, s25, -v175
	v_add_f32_e32 v6, v20, v6
	v_mul_f32_e32 v7, 0x3fb8aa3b, v7
	v_add_f32_e32 v6, v21, v6
	v_exp_f32_e32 v14, v7
	v_fma_f32 v7, v69, s25, -v175
	v_add_f32_e32 v6, v22, v6
	v_mul_f32_e32 v7, 0x3fb8aa3b, v7
	v_add_f32_e32 v6, v23, v6
	v_exp_f32_e32 v15, v7
	v_fma_f32 v7, v70, s25, -v175
	v_add_f32_e32 v6, v24, v6
	v_mul_f32_e32 v7, 0x3fb8aa3b, v7
	v_add_f32_e32 v6, v25, v6
	v_exp_f32_e32 v16, v7
	v_fma_f32 v7, v71, s25, -v175
	v_add_f32_e32 v6, v26, v6
	v_mul_f32_e32 v7, 0x3fb8aa3b, v7
	v_add_f32_e32 v6, v27, v6
	v_exp_f32_e32 v17, v7
	v_fma_f32 v7, v72, s25, -v175
	v_add_f32_e32 v6, v12, v6
	v_mul_f32_e32 v7, 0x3fb8aa3b, v7
	v_add_f32_e32 v6, v13, v6
	v_exp_f32_e32 v18, v7
	v_fma_f32 v7, v73, s25, -v175
	v_add_f32_e32 v6, v14, v6
	v_mul_f32_e32 v7, 0x3fb8aa3b, v7
	v_add_f32_e32 v6, v15, v6
	v_exp_f32_e32 v19, v7
	v_add_f32_e32 v6, v16, v6
	v_add_f32_e32 v6, v17, v6
	v_add_f32_e32 v6, v18, v6
	v_add_f32_e32 v7, v19, v6
	v_fma_f32 v6, v74, s25, -v175
	v_mul_f32_e32 v6, 0x3fb8aa3b, v6
	v_exp_f32_e32 v6, v6
	v_cvt_pk_bf16_f32 v44, v94, v95
	v_cvt_pk_bf16_f32 v45, v96, v97
	v_cvt_pk_bf16_f32 v46, v133, v135
	v_cvt_pk_bf16_f32 v47, v136, v137
	ds_read2_b64 v[48:51], v144 offset1:4
	v_add_f32_e32 v8, v6, v7
	v_fma_f32 v7, v75, s25, -v175
	ds_read2_b64 v[52:55], v145 offset0:2 offset1:6
	ds_read2_b64 v[56:59], v146 offset0:4 offset1:8
	ds_read2_b64 v[60:63], v147 offset0:6 offset1:10
	ds_read2_b64 v[64:67], v148 offset0:8 offset1:12
	ds_read2_b64 v[68:71], v149 offset0:10 offset1:14
	ds_read2_b64 v[72:75], v150 offset0:12 offset1:16
	ds_read2_b64 v[94:97], v151 offset0:14 offset1:18
	v_cvt_pk_bf16_f32 v86, v86, v87
	v_cvt_pk_bf16_f32 v87, v88, v89
	v_cvt_pk_bf16_f32 v88, v90, v91
	v_cvt_pk_bf16_f32 v89, v92, v93
	ds_read2_b64 v[90:93], v144 offset0:8 offset1:12
	s_waitcnt lgkmcnt(8)
	v_mfma_f32_16x16x32_bf16 v[48:51], v[48:51], v[44:47], 0
	v_mul_f32_e32 v7, 0x3fb8aa3b, v7
	v_exp_f32_e32 v7, v7
	v_fma_f32 v2, v2, s25, -v175
	s_waitcnt lgkmcnt(0)
	v_mfma_f32_16x16x32_bf16 v[48:51], v[90:93], v[86:89], v[48:51]
	ds_read2_b64 v[90:93], v145 offset0:10 offset1:14
	v_add_f32_e32 v9, v7, v8
	v_fma_f32 v8, v76, s25, -v175
	v_mfma_f32_16x16x32_bf16 v[52:55], v[52:55], v[44:47], 0
	v_mul_f32_e32 v8, 0x3fb8aa3b, v8
	v_exp_f32_e32 v8, v8
	v_mul_f32_e32 v2, 0x3fb8aa3b, v2
	s_waitcnt lgkmcnt(0)
	v_mfma_f32_16x16x32_bf16 v[52:55], v[90:93], v[86:89], v[52:55]
	ds_read2_b64 v[90:93], v146 offset0:12 offset1:16
	v_add_f32_e32 v10, v8, v9
	v_fma_f32 v9, v77, s25, -v175
	v_mfma_f32_16x16x32_bf16 v[56:59], v[56:59], v[44:47], 0
	v_mul_f32_e32 v9, 0x3fb8aa3b, v9
	v_exp_f32_e32 v9, v9
	v_fma_f32 v3, v3, s25, -v175
	s_waitcnt lgkmcnt(0)
	v_mfma_f32_16x16x32_bf16 v[56:59], v[90:93], v[86:89], v[56:59]
	ds_read2_b64 v[90:93], v147 offset0:14 offset1:18
	v_add_f32_e32 v11, v9, v10
	v_exp_f32_e32 v10, v2
	v_mfma_f32_16x16x32_bf16 v[60:63], v[60:63], v[44:47], 0
	v_mul_f32_e32 v3, 0x3fb8aa3b, v3
	v_mov_b32_e32 v133, v99
	v_add_f32_e32 v2, v10, v11
	s_waitcnt lgkmcnt(0)
	v_mfma_f32_16x16x32_bf16 v[60:63], v[90:93], v[86:89], v[60:63]
	ds_read2_b64 v[90:93], v148 offset0:16 offset1:20
	v_exp_f32_e32 v11, v3
	v_fma_f32 v3, v4, s25, -v175
	v_mfma_f32_16x16x32_bf16 v[64:67], v[64:67], v[44:47], 0
	v_mul_f32_e32 v3, 0x3fb8aa3b, v3
	v_exp_f32_e32 v4, v3
	v_fma_f32 v3, v5, s25, -v175
	s_waitcnt lgkmcnt(0)
	v_mfma_f32_16x16x32_bf16 v[64:67], v[90:93], v[86:89], v[64:67]
	ds_read2_b64 v[90:93], v149 offset0:18 offset1:22
	v_mul_f32_e32 v3, 0x3fb8aa3b, v3
	v_exp_f32_e32 v5, v3
	v_mfma_f32_16x16x32_bf16 v[68:71], v[68:71], v[44:47], 0
	v_add_f32_e32 v2, v11, v2
	v_add_f32_e32 v2, v4, v2
	v_add_f32_e32 v2, v5, v2
	s_waitcnt lgkmcnt(0)
	v_mfma_f32_16x16x32_bf16 v[68:71], v[90:93], v[86:89], v[68:71]
	ds_read2_b64 v[90:93], v150 offset0:20 offset1:24
	ds_bpermute_b32 v3, v138, v2
	v_mov_b32_e32 v135, v99
	v_mfma_f32_16x16x32_bf16 v[72:75], v[72:75], v[44:47], 0
	s_waitcnt lgkmcnt(0)
	v_add_f32_e32 v2, v2, v3
	v_mfma_f32_16x16x32_bf16 v[72:75], v[90:93], v[86:89], v[72:75]
	ds_read2_b64 v[90:93], v151 offset0:22 offset1:26
	v_cvt_pk_bf16_f32 v76, v78, v79
	v_cvt_pk_bf16_f32 v77, v80, v81
	v_cvt_pk_bf16_f32 v78, v82, v83
	v_cvt_pk_bf16_f32 v79, v84, v85
	ds_read2_b64 v[80:83], v144 offset0:16 offset1:20
	s_waitcnt lgkmcnt(0)
	v_mfma_f32_16x16x32_bf16 v[48:51], v[80:83], v[76:79], v[48:51]
	ds_read2_b64 v[80:83], v145 offset0:18 offset1:22
	ds_bpermute_b32 v3, v139, v2
	s_waitcnt lgkmcnt(0)
	v_add_f32_e32 v2, v2, v3
	v_mfma_f32_16x16x32_bf16 v[52:55], v[80:83], v[76:79], v[52:55]
	ds_read2_b64 v[80:83], v146 offset0:20 offset1:24
	v_div_scale_f32 v3, s[12:13], v2, v2, 1.0
	s_waitcnt lgkmcnt(0)
	v_mfma_f32_16x16x32_bf16 v[56:59], v[80:83], v[76:79], v[56:59]
	ds_read2_b64 v[80:83], v147 offset0:22 offset1:26
	s_waitcnt lgkmcnt(0)
	v_mfma_f32_16x16x32_bf16 v[60:63], v[80:83], v[76:79], v[60:63]
	ds_read2_b64 v[80:83], v148 offset0:24 offset1:28
	s_waitcnt lgkmcnt(0)
	v_mfma_f32_16x16x32_bf16 v[64:67], v[80:83], v[76:79], v[64:67]
	ds_read2_b64 v[80:83], v149 offset0:26 offset1:30
	s_waitcnt lgkmcnt(0)
	v_mfma_f32_16x16x32_bf16 v[68:71], v[80:83], v[76:79], v[68:71]
	ds_read2_b64 v[80:83], v150 offset0:28 offset1:32
	s_waitcnt lgkmcnt(0)
	v_mfma_f32_16x16x32_bf16 v[72:75], v[80:83], v[76:79], v[72:75]
	ds_read2_b64 v[80:83], v151 offset0:30 offset1:34
	v_cvt_pk_bf16_f32 v36, v36, v37
	v_cvt_pk_bf16_f32 v37, v38, v39
	v_cvt_pk_bf16_f32 v38, v40, v41
	v_cvt_pk_bf16_f32 v39, v42, v43
	ds_read2_b64 v[40:43], v144 offset0:24 offset1:28
	s_waitcnt lgkmcnt(0)
	v_mfma_f32_16x16x32_bf16 v[40:43], v[40:43], v[36:39], v[48:51]
	s_nop 2
	ds_read2_b64 v[48:51], v145 offset0:26 offset1:30
	s_waitcnt lgkmcnt(0)
	v_mfma_f32_16x16x32_bf16 v[48:51], v[48:51], v[36:39], v[52:55]
	s_nop 2
	ds_read2_b64 v[52:55], v146 offset0:28 offset1:32
	s_waitcnt lgkmcnt(0)
	v_mfma_f32_16x16x32_bf16 v[52:55], v[52:55], v[36:39], v[56:59]
	s_nop 2
	ds_read2_b64 v[56:59], v147 offset0:30 offset1:34
	s_waitcnt lgkmcnt(0)
	v_mfma_f32_16x16x32_bf16 v[56:59], v[56:59], v[36:39], v[60:63]
	s_nop 2
	ds_read2_b64 v[60:63], v148 offset0:32 offset1:36
	s_waitcnt lgkmcnt(0)
	v_mfma_f32_16x16x32_bf16 v[60:63], v[60:63], v[36:39], v[64:67]
	s_nop 2
	ds_read2_b64 v[64:67], v149 offset0:34 offset1:38
	s_waitcnt lgkmcnt(0)
	v_mfma_f32_16x16x32_bf16 v[64:67], v[64:67], v[36:39], v[68:71]
	s_nop 2
	ds_read2_b64 v[68:71], v150 offset0:36 offset1:40
	s_waitcnt lgkmcnt(0)
	v_mfma_f32_16x16x32_bf16 v[68:71], v[68:71], v[36:39], v[72:75]
	s_nop 2
	ds_read2_b64 v[72:75], v151 offset0:38 offset1:42
	v_cvt_pk_bf16_f32 v28, v28, v29
	v_cvt_pk_bf16_f32 v29, v30, v31
	v_cvt_pk_bf16_f32 v30, v32, v33
	v_cvt_pk_bf16_f32 v31, v34, v35
	ds_read2_b64 v[32:35], v144 offset0:32 offset1:36
	v_mfma_f32_16x16x32_bf16 v[44:47], v[94:97], v[44:47], 0
	s_waitcnt lgkmcnt(0)
	v_mfma_f32_16x16x32_bf16 v[32:35], v[32:35], v[28:31], v[40:43]
	s_nop 2
	ds_read2_b64 v[40:43], v145 offset0:34 offset1:38
	v_mfma_f32_16x16x32_bf16 v[44:47], v[90:93], v[86:89], v[44:47]
	v_mfma_f32_16x16x32_bf16 v[44:47], v[80:83], v[76:79], v[44:47]
	v_mfma_f32_16x16x32_bf16 v[36:39], v[72:75], v[36:39], v[44:47]
	s_waitcnt lgkmcnt(0)
	v_mfma_f32_16x16x32_bf16 v[40:43], v[40:43], v[28:31], v[48:51]
	s_nop 4
	ds_read2_b64 v[44:47], v146 offset0:36 offset1:40
	ds_read2_b64 v[48:51], v147 offset0:38 offset1:42
	s_waitcnt lgkmcnt(1)
	v_mfma_f32_16x16x32_bf16 v[44:47], v[44:47], v[28:31], v[52:55]
	s_nop 2
	ds_read2_b64 v[52:55], v148 offset0:40 offset1:44
	s_waitcnt lgkmcnt(1)
	v_mfma_f32_16x16x32_bf16 v[48:51], v[48:51], v[28:31], v[56:59]
	s_nop 2
	ds_read2_b64 v[56:59], v149 offset0:42 offset1:46
	s_waitcnt lgkmcnt(1)
	v_mfma_f32_16x16x32_bf16 v[52:55], v[52:55], v[28:31], v[60:63]
	s_nop 2
	ds_read2_b64 v[60:63], v150 offset0:44 offset1:48
	s_waitcnt lgkmcnt(1)
	v_mfma_f32_16x16x32_bf16 v[56:59], v[56:59], v[28:31], v[64:67]
	s_nop 2
	ds_read2_b64 v[64:67], v151 offset0:46 offset1:50
	v_cvt_pk_bf16_f32 v20, v20, v21
	v_cvt_pk_bf16_f32 v21, v22, v23
	v_cvt_pk_bf16_f32 v22, v24, v25
	v_cvt_pk_bf16_f32 v23, v26, v27
	ds_read2_b64 v[24:27], v144 offset0:40 offset1:44
	s_waitcnt lgkmcnt(0)
	v_mfma_f32_16x16x32_bf16 v[24:27], v[24:27], v[20:23], v[32:35]
	s_nop 2
	ds_read2_b64 v[32:35], v145 offset0:42 offset1:46
	v_mfma_f32_16x16x32_bf16 v[60:63], v[60:63], v[28:31], v[68:71]
	v_mfma_f32_16x16x32_bf16 v[28:31], v[64:67], v[28:31], v[36:39]
	s_waitcnt lgkmcnt(0)
	v_mfma_f32_16x16x32_bf16 v[32:35], v[32:35], v[20:23], v[40:43]
	s_nop 0
	ds_read2_b64 v[36:39], v146 offset0:44 offset1:48
	s_nop 0
	ds_read2_b64 v[40:43], v147 offset0:46 offset1:50
	s_waitcnt lgkmcnt(1)
	v_mfma_f32_16x16x32_bf16 v[36:39], v[36:39], v[20:23], v[44:47]
	s_nop 2
	ds_read2_b64 v[44:47], v148 offset0:48 offset1:52
	s_waitcnt lgkmcnt(1)
	v_mfma_f32_16x16x32_bf16 v[40:43], v[40:43], v[20:23], v[48:51]
	s_nop 2
	ds_read2_b64 v[48:51], v149 offset0:50 offset1:54
	s_waitcnt lgkmcnt(1)
	v_mfma_f32_16x16x32_bf16 v[44:47], v[44:47], v[20:23], v[52:55]
	s_nop 2
	ds_read2_b64 v[52:55], v150 offset0:52 offset1:56
	s_waitcnt lgkmcnt(1)
	v_mfma_f32_16x16x32_bf16 v[48:51], v[48:51], v[20:23], v[56:59]
	s_nop 2
	ds_read_b64 v[56:57], v151 offset:432
	ds_read_b64 v[58:59], v152
	v_cvt_pk_bf16_f32 v12, v12, v13
	v_cvt_pk_bf16_f32 v13, v14, v15
	v_cvt_pk_bf16_f32 v14, v16, v17
	v_cvt_pk_bf16_f32 v15, v18, v19
	ds_read2_b64 v[16:19], v144 offset0:48 offset1:52
	s_waitcnt lgkmcnt(0)
	v_mfma_f32_16x16x32_bf16 v[16:19], v[16:19], v[12:15], v[24:27]
	s_nop 2
	ds_read2_b64 v[24:27], v145 offset0:50 offset1:54
	v_mfma_f32_16x16x32_bf16 v[52:55], v[52:55], v[20:23], v[60:63]
	v_mfma_f32_16x16x32_bf16 v[20:23], v[56:59], v[20:23], v[28:31]
	s_nop 2
	ds_read2_b64 v[28:31], v146 offset0:52 offset1:56
	s_waitcnt lgkmcnt(1)
	v_mfma_f32_16x16x32_bf16 v[24:27], v[24:27], v[12:15], v[32:35]
	s_nop 2
	ds_read_b64 v[32:33], v147 offset:432
	ds_read_b64 v[34:35], v153
	s_waitcnt lgkmcnt(2)
	v_mfma_f32_16x16x32_bf16 v[28:31], v[28:31], v[12:15], v[36:39]
	s_nop 2
	ds_read_b64 v[36:37], v148 offset:448
	ds_read_b64 v[38:39], v154
	s_waitcnt lgkmcnt(2)
	v_mfma_f32_16x16x32_bf16 v[32:35], v[32:35], v[12:15], v[40:43]
	s_nop 2
	ds_read_b64 v[40:41], v155
	ds_read_b64 v[42:43], v156
	s_waitcnt lgkmcnt(2)
	v_mfma_f32_16x16x32_bf16 v[36:39], v[36:39], v[12:15], v[44:47]
	s_nop 2
	ds_read_b64 v[44:45], v157
	ds_read_b64 v[46:47], v150
	s_waitcnt lgkmcnt(2)
	v_mfma_f32_16x16x32_bf16 v[40:43], v[40:43], v[12:15], v[48:51]
	s_nop 2
	ds_read_b64 v[48:49], v158
	ds_read_b64 v[50:51], v151 offset:16
	v_cvt_pk_bf16_f32 v6, v6, v7
	v_cvt_pk_bf16_f32 v7, v8, v9
	s_waitcnt lgkmcnt(2)
	v_mfma_f32_16x16x32_bf16 v[44:47], v[44:47], v[12:15], v[52:55]
	v_cvt_pk_bf16_f32 v8, v10, v11
	v_cvt_pk_bf16_f32 v9, v4, v5
	s_waitcnt lgkmcnt(0)
	v_mfma_f32_16x16x32_bf16 v[12:15], v[48:51], v[12:15], v[20:23]
	s_nop 2
	ds_read_b64 v[20:21], v144 offset:448
	ds_read_b64 v[22:23], v159
	s_waitcnt lgkmcnt(0)
	v_mfma_f32_16x16x32_bf16 v[16:19], v[20:23], v[6:9], v[16:19]
	ds_read_b64 v[20:21], v145 offset:464
	ds_read_b64 v[22:23], v160
	s_waitcnt lgkmcnt(0)
	v_mfma_f32_16x16x32_bf16 v[20:23], v[20:23], v[6:9], v[24:27]
	s_nop 2
	ds_read_b64 v[24:25], v161
	ds_read_b64 v[26:27], v146
	s_waitcnt lgkmcnt(0)
	v_mfma_f32_16x16x32_bf16 v[24:27], v[24:27], v[6:9], v[28:31]
	s_nop 2
	ds_read_b64 v[28:29], v162
	ds_read_b64 v[30:31], v147 offset:16
	s_waitcnt lgkmcnt(0)
	v_mfma_f32_16x16x32_bf16 v[28:31], v[28:31], v[6:9], v[32:35]
	s_nop 2
	ds_read2_b64 v[32:35], v148 offset1:4
	s_waitcnt lgkmcnt(0)
	v_mfma_f32_16x16x32_bf16 v[32:35], v[32:35], v[6:9], v[36:39]
	s_nop 2
	ds_read2_b64 v[36:39], v149 offset0:2 offset1:6
	s_waitcnt lgkmcnt(0)
	v_mfma_f32_16x16x32_bf16 v[36:39], v[36:39], v[6:9], v[40:43]
	s_nop 2
	ds_read2_b64 v[40:43], v150 offset0:4 offset1:8
	s_waitcnt lgkmcnt(0)
	v_mfma_f32_16x16x32_bf16 v[40:43], v[40:43], v[6:9], v[44:47]
	s_nop 2
	ds_read2_b64 v[44:47], v151 offset0:6 offset1:10
	s_waitcnt lgkmcnt(0)
	v_mfma_f32_16x16x32_bf16 v[4:7], v[44:47], v[6:9], v[12:15]
	v_rcp_f32_e32 v8, v3
	s_nop 0
	v_fma_f32 v9, -v3, v8, 1.0
	v_fmac_f32_e32 v8, v9, v8
	v_div_scale_f32 v9, vcc, 1.0, v2, 1.0
	v_mul_f32_e32 v10, v9, v8
	v_fma_f32 v11, -v3, v10, v9
	v_fmac_f32_e32 v10, v11, v8
	v_fma_f32 v3, -v3, v10, v9
	v_div_fmas_f32 v3, v3, v8, v10
	v_div_fixup_f32 v10, v3, v2, 1.0
	v_mul_f32_e32 v8, v10, v16
	v_mul_f32_e32 v9, v10, v17
	v_lshl_add_u64 v[2:3], s[0:1], 0, v[132:133]
	v_cvt_pk_bf16_f32 v8, v8, v9
	v_mul_f32_e32 v9, v10, v18
	v_lshl_add_u64 v[2:3], v[2:3], 0, v[134:135]
	v_mul_f32_e32 v11, v10, v19
	v_cvt_pk_bf16_f32 v9, v9, v11
	global_store_dwordx2 v[2:3], v[8:9], off
	v_mul_f32_e32 v8, v10, v20
	v_mul_f32_e32 v9, v10, v21
	v_cvt_pk_bf16_f32 v8, v8, v9
	v_mul_f32_e32 v9, v10, v22
	v_mul_f32_e32 v11, v10, v23
	v_cvt_pk_bf16_f32 v9, v9, v11
	global_store_dwordx2 v[2:3], v[8:9], off offset:32
	v_mul_f32_e32 v8, v10, v24
	v_mul_f32_e32 v9, v10, v25
	v_cvt_pk_bf16_f32 v8, v8, v9
	v_mul_f32_e32 v9, v10, v26
	v_mul_f32_e32 v11, v10, v27
	v_cvt_pk_bf16_f32 v9, v9, v11
	global_store_dwordx2 v[2:3], v[8:9], off offset:64
	v_mul_f32_e32 v8, v10, v28
	v_mul_f32_e32 v9, v10, v29
	v_cvt_pk_bf16_f32 v8, v8, v9
	v_mul_f32_e32 v9, v10, v30
	v_mul_f32_e32 v11, v10, v31
	v_cvt_pk_bf16_f32 v9, v9, v11
	global_store_dwordx2 v[2:3], v[8:9], off offset:96
	v_mul_f32_e32 v8, v10, v32
	v_mul_f32_e32 v9, v10, v33
	v_cvt_pk_bf16_f32 v8, v8, v9
	v_mul_f32_e32 v9, v10, v34
	v_mul_f32_e32 v11, v10, v35
	v_cvt_pk_bf16_f32 v9, v9, v11
	global_store_dwordx2 v[2:3], v[8:9], off offset:128
	v_mul_f32_e32 v8, v10, v36
	v_mul_f32_e32 v9, v10, v37
	v_cvt_pk_bf16_f32 v8, v8, v9
	v_mul_f32_e32 v9, v10, v38
	v_mul_f32_e32 v11, v10, v39
	v_cvt_pk_bf16_f32 v9, v9, v11
	global_store_dwordx2 v[2:3], v[8:9], off offset:160
	v_mul_f32_e32 v8, v10, v40
	v_mul_f32_e32 v9, v10, v41
	v_cvt_pk_bf16_f32 v8, v8, v9
	v_mul_f32_e32 v9, v10, v42
	v_mul_f32_e32 v4, v10, v4
	v_mul_f32_e32 v5, v10, v5
	v_mul_f32_e32 v11, v10, v43
	v_cvt_pk_bf16_f32 v9, v9, v11
	global_store_dwordx2 v[2:3], v[8:9], off offset:192
	v_cvt_pk_bf16_f32 v4, v4, v5
	v_mul_f32_e32 v5, v10, v6
	v_mul_f32_e32 v6, v10, v7
	v_cvt_pk_bf16_f32 v5, v5, v6
	global_store_dwordx2 v[2:3], v[4:5], off offset:224
	s_cbranch_scc1 .LBB0_1113
